# s_setprio strategy: all per-phase priority flips removed from the kernel (both wave halves at default priority)
# speedup vs baseline: 1.0069x; 1.0012x over previous
.LBB0_327:
	ds_read_b128 v[154:157], v150
	ds_read_b128 v[158:161], v150 offset:1024
	ds_read_b128 v[164:167], v150 offset:2048
	ds_read_b128 v[168:171], v150 offset:3072
	ds_read_b128 v[172:175], v151
	ds_read_b128 v[176:179], v151 offset:1024
	ds_read_b128 v[180:183], v151 offset:2048
	ds_read_b128 v[184:187], v151 offset:3072
	s_add_u32 s24, s40, 0xfff80080
	s_addc_u32 s25, s41, -1
	s_cmp_eq_u32 s61, 28
	s_cselect_b32 s45, s13, s25
	s_cselect_b32 s44, s15, s24
	s_cselect_b32 s43, s57, s60
	s_cselect_b32 s42, s58, s59
	v_lshl_add_u64 v[146:147], s[40:41], 0, v[138:139]
	s_add_i32 m0, s39, 0xc000
	ds_read_b128 v[188:191], v152
	ds_read_b128 v[192:195], v152 offset:1024
	ds_read_b128 v[196:199], v152 offset:2048
	ds_read_b128 v[200:203], v152 offset:3072
	ds_read_b128 v[204:207], v152 offset:4096
	ds_read_b128 v[208:211], v152 offset:5120
	ds_read_b128 v[212:215], v152 offset:6144
	ds_read_b128 v[216:219], v152 offset:7168
	global_load_lds_dwordx4 v[146:147], off
	v_lshl_add_u64 v[146:147], s[40:41], 0, v[140:141]
	s_add_i32 m0, s39, 0xe000
	s_nop 0
	global_load_lds_dwordx4 v[146:147], off
	s_waitcnt vmcnt(8)
	s_waitcnt lgkmcnt(0)
	s_barrier
	s_waitcnt lgkmcnt(0)
	v_mfma_f32_16x16x32_bf16 v[126:129], v[154:157], v[188:191], v[126:129]
	v_mfma_f32_16x16x32_bf16 v[122:125], v[164:167], v[188:191], v[122:125]
	v_mfma_f32_16x16x32_bf16 v[110:113], v[154:157], v[196:199], v[110:113]
	v_mfma_f32_16x16x32_bf16 v[106:109], v[164:167], v[196:199], v[106:109]
	v_mfma_f32_16x16x32_bf16 v[94:97], v[154:157], v[204:207], v[94:97]
	v_mfma_f32_16x16x32_bf16 v[90:93], v[164:167], v[204:207], v[90:93]
	v_mfma_f32_16x16x32_bf16 v[78:81], v[154:157], v[212:215], v[78:81]
	v_mfma_f32_16x16x32_bf16 v[74:77], v[164:167], v[212:215], v[74:77]
	v_mfma_f32_16x16x32_bf16 v[126:129], v[158:161], v[192:195], v[126:129]
	v_mfma_f32_16x16x32_bf16 v[122:125], v[168:171], v[192:195], v[122:125]
	v_mfma_f32_16x16x32_bf16 v[110:113], v[158:161], v[200:203], v[110:113]
	v_mfma_f32_16x16x32_bf16 v[106:109], v[168:171], v[200:203], v[106:109]
	v_mfma_f32_16x16x32_bf16 v[94:97], v[158:161], v[208:211], v[94:97]
	v_mfma_f32_16x16x32_bf16 v[90:93], v[168:171], v[208:211], v[90:93]
	v_mfma_f32_16x16x32_bf16 v[78:81], v[158:161], v[216:219], v[78:81]
	v_mfma_f32_16x16x32_bf16 v[74:77], v[168:171], v[216:219], v[74:77]
	v_mfma_f32_16x16x32_bf16 v[118:121], v[172:175], v[188:191], v[118:121]
	v_mfma_f32_16x16x32_bf16 v[114:117], v[180:183], v[188:191], v[114:117]
	v_mfma_f32_16x16x32_bf16 v[102:105], v[172:175], v[196:199], v[102:105]
	v_mfma_f32_16x16x32_bf16 v[98:101], v[180:183], v[196:199], v[98:101]
	v_mfma_f32_16x16x32_bf16 v[86:89], v[172:175], v[204:207], v[86:89]
	v_mfma_f32_16x16x32_bf16 v[82:85], v[180:183], v[204:207], v[82:85]
	v_mfma_f32_16x16x32_bf16 v[70:73], v[172:175], v[212:215], v[70:73]
	v_mfma_f32_16x16x32_bf16 v[66:69], v[180:183], v[212:215], v[66:69]
	v_mfma_f32_16x16x32_bf16 v[118:121], v[176:179], v[192:195], v[118:121]
	v_mfma_f32_16x16x32_bf16 v[114:117], v[184:187], v[192:195], v[114:117]
	v_mfma_f32_16x16x32_bf16 v[102:105], v[176:179], v[200:203], v[102:105]
	v_mfma_f32_16x16x32_bf16 v[98:101], v[184:187], v[200:203], v[98:101]
	v_mfma_f32_16x16x32_bf16 v[86:89], v[176:179], v[208:211], v[86:89]
	v_mfma_f32_16x16x32_bf16 v[82:85], v[184:187], v[208:211], v[82:85]
	v_mfma_f32_16x16x32_bf16 v[70:73], v[176:179], v[216:219], v[70:73]
	v_mfma_f32_16x16x32_bf16 v[66:69], v[184:187], v[216:219], v[66:69]
	s_barrier
	s_add_i32 s24, s53, s21
	v_lshl_add_u64 v[146:147], s[42:43], 0, v[132:133]
	s_mov_b32 m0, s24
	ds_read_b128 v[188:191], v152 offset:16384
	ds_read_b128 v[192:195], v152 offset:17408
	ds_read_b128 v[196:199], v152 offset:18432
	ds_read_b128 v[200:203], v152 offset:19456
	ds_read_b128 v[204:207], v152 offset:20480
	ds_read_b128 v[208:211], v152 offset:21504
	ds_read_b128 v[212:215], v152 offset:22528
	ds_read_b128 v[216:219], v152 offset:23552
	global_load_lds_dwordx4 v[146:147], off
	s_add_i32 m0, s24, 0x2000
	s_add_u32 s24, s42, 0x80000
	v_lshl_add_u64 v[220:221], s[42:43], 0, v[136:137]
	s_addc_u32 s25, s43, 0
	s_add_i32 s62, s54, s21
	global_load_lds_dwordx4 v[220:221], off
	v_lshl_add_u64 v[222:223], s[24:25], 0, v[132:133]
	s_mov_b32 m0, s62
	v_lshl_add_u64 v[224:225], s[44:45], 0, v[134:135]
	global_load_lds_dwordx4 v[222:223], off
	v_lshl_add_u64 v[222:223], s[24:25], 0, v[136:137]
	s_add_i32 m0, s62, 0x2000
	s_nop 0
	global_load_lds_dwordx4 v[222:223], off
	v_lshl_add_u64 v[222:223], s[44:45], 0, v[130:131]
	s_mov_b32 m0, s39
	s_nop 0
	global_load_lds_dwordx4 v[222:223], off
	s_mov_b32 m0, s46
	s_nop 0
	global_load_lds_dwordx4 v[224:225], off
	s_waitcnt vmcnt(8)
	s_waitcnt lgkmcnt(0)
	s_barrier
	s_waitcnt lgkmcnt(0)
	v_mfma_f32_16x16x32_bf16 v[62:65], v[154:157], v[188:191], v[62:65]
	v_mfma_f32_16x16x32_bf16 v[58:61], v[164:167], v[188:191], v[58:61]
	v_mfma_f32_16x16x32_bf16 v[46:49], v[154:157], v[196:199], v[46:49]
	v_mfma_f32_16x16x32_bf16 v[42:45], v[164:167], v[196:199], v[42:45]
	v_mfma_f32_16x16x32_bf16 v[30:33], v[154:157], v[204:207], v[30:33]
	v_mfma_f32_16x16x32_bf16 v[26:29], v[164:167], v[204:207], v[26:29]
	v_mfma_f32_16x16x32_bf16 v[14:17], v[154:157], v[212:215], v[14:17]
	v_mfma_f32_16x16x32_bf16 v[10:13], v[164:167], v[212:215], v[10:13]
	v_mfma_f32_16x16x32_bf16 v[62:65], v[158:161], v[192:195], v[62:65]
	v_mfma_f32_16x16x32_bf16 v[58:61], v[168:171], v[192:195], v[58:61]
	v_mfma_f32_16x16x32_bf16 v[46:49], v[158:161], v[200:203], v[46:49]
	v_mfma_f32_16x16x32_bf16 v[42:45], v[168:171], v[200:203], v[42:45]
	v_mfma_f32_16x16x32_bf16 v[30:33], v[158:161], v[208:211], v[30:33]
	v_mfma_f32_16x16x32_bf16 v[26:29], v[168:171], v[208:211], v[26:29]
	v_mfma_f32_16x16x32_bf16 v[14:17], v[158:161], v[216:219], v[14:17]
	v_mfma_f32_16x16x32_bf16 v[10:13], v[168:171], v[216:219], v[10:13]
	v_mfma_f32_16x16x32_bf16 v[54:57], v[172:175], v[188:191], v[54:57]
	v_mfma_f32_16x16x32_bf16 v[50:53], v[180:183], v[188:191], v[50:53]
	v_mfma_f32_16x16x32_bf16 v[38:41], v[172:175], v[196:199], v[38:41]
	v_mfma_f32_16x16x32_bf16 v[34:37], v[180:183], v[196:199], v[34:37]
	v_mfma_f32_16x16x32_bf16 v[22:25], v[172:175], v[204:207], v[22:25]
	v_mfma_f32_16x16x32_bf16 v[18:21], v[180:183], v[204:207], v[18:21]
	v_mfma_f32_16x16x32_bf16 v[6:9], v[172:175], v[212:215], v[6:9]
	v_mfma_f32_16x16x32_bf16 v[2:5], v[180:183], v[212:215], v[2:5]
	v_mfma_f32_16x16x32_bf16 v[54:57], v[176:179], v[192:195], v[54:57]
	v_mfma_f32_16x16x32_bf16 v[50:53], v[184:187], v[192:195], v[50:53]
	v_mfma_f32_16x16x32_bf16 v[38:41], v[176:179], v[200:203], v[38:41]
	v_mfma_f32_16x16x32_bf16 v[34:37], v[184:187], v[200:203], v[34:37]
	v_mfma_f32_16x16x32_bf16 v[22:25], v[176:179], v[208:211], v[22:25]
	v_mfma_f32_16x16x32_bf16 v[18:21], v[184:187], v[208:211], v[18:21]
	v_mfma_f32_16x16x32_bf16 v[6:9], v[176:179], v[216:219], v[6:9]
	v_mfma_f32_16x16x32_bf16 v[2:5], v[184:187], v[216:219], v[2:5]
	s_barrier
	s_add_i32 s62, 0, 0x18000
	v_add_u32_e32 v153, s62, v148
	s_add_i32 s63, 0, 0x1c000
	ds_read_b128 v[154:157], v153
	ds_read_b128 v[158:161], v153 offset:1024
	ds_read_b128 v[164:167], v153 offset:2048
	ds_read_b128 v[168:171], v153 offset:3072
	v_add_u32_e32 v153, s63, v148
	ds_read_b128 v[172:175], v153
	ds_read_b128 v[176:179], v153 offset:1024
	ds_read_b128 v[180:183], v153 offset:2048
	ds_read_b128 v[184:187], v153 offset:3072
	s_add_u32 s24, s44, 0x80000
	s_addc_u32 s25, s45, 0
	s_mov_b32 m0, s47
	v_lshl_add_u64 v[226:227], s[24:25], 0, v[130:131]
	ds_read_b128 v[188:191], v152 offset:32768
	ds_read_b128 v[192:195], v152 offset:33792
	ds_read_b128 v[196:199], v152 offset:34816
	ds_read_b128 v[200:203], v152 offset:35840
	ds_read_b128 v[204:207], v152 offset:36864
	ds_read_b128 v[208:211], v152 offset:37888
	ds_read_b128 v[212:215], v152 offset:38912
	ds_read_b128 v[216:219], v152 offset:39936
	global_load_lds_dwordx4 v[226:227], off
	v_lshl_add_u64 v[226:227], s[24:25], 0, v[134:135]
	s_mov_b32 m0, s48
	s_nop 0
	global_load_lds_dwordx4 v[226:227], off
	s_waitcnt vmcnt(8)
	s_waitcnt lgkmcnt(0)
	s_barrier
	s_waitcnt lgkmcnt(0)
	v_mfma_f32_16x16x32_bf16 v[126:129], v[154:157], v[188:191], v[126:129]
	v_mfma_f32_16x16x32_bf16 v[122:125], v[164:167], v[188:191], v[122:125]
	v_mfma_f32_16x16x32_bf16 v[110:113], v[154:157], v[196:199], v[110:113]
	v_mfma_f32_16x16x32_bf16 v[106:109], v[164:167], v[196:199], v[106:109]
	v_mfma_f32_16x16x32_bf16 v[94:97], v[154:157], v[204:207], v[94:97]
	v_mfma_f32_16x16x32_bf16 v[90:93], v[164:167], v[204:207], v[90:93]
	v_mfma_f32_16x16x32_bf16 v[78:81], v[154:157], v[212:215], v[78:81]
	v_mfma_f32_16x16x32_bf16 v[74:77], v[164:167], v[212:215], v[74:77]
	v_mfma_f32_16x16x32_bf16 v[126:129], v[158:161], v[192:195], v[126:129]
	v_mfma_f32_16x16x32_bf16 v[122:125], v[168:171], v[192:195], v[122:125]
	v_mfma_f32_16x16x32_bf16 v[110:113], v[158:161], v[200:203], v[110:113]
	v_mfma_f32_16x16x32_bf16 v[106:109], v[168:171], v[200:203], v[106:109]
	v_mfma_f32_16x16x32_bf16 v[94:97], v[158:161], v[208:211], v[94:97]
	v_mfma_f32_16x16x32_bf16 v[90:93], v[168:171], v[208:211], v[90:93]
	v_mfma_f32_16x16x32_bf16 v[78:81], v[158:161], v[216:219], v[78:81]
	v_mfma_f32_16x16x32_bf16 v[74:77], v[168:171], v[216:219], v[74:77]
	v_mfma_f32_16x16x32_bf16 v[118:121], v[172:175], v[188:191], v[118:121]
	v_mfma_f32_16x16x32_bf16 v[114:117], v[180:183], v[188:191], v[114:117]
	v_mfma_f32_16x16x32_bf16 v[102:105], v[172:175], v[196:199], v[102:105]
	v_mfma_f32_16x16x32_bf16 v[98:101], v[180:183], v[196:199], v[98:101]
	v_mfma_f32_16x16x32_bf16 v[86:89], v[172:175], v[204:207], v[86:89]
	v_mfma_f32_16x16x32_bf16 v[82:85], v[180:183], v[204:207], v[82:85]
	v_mfma_f32_16x16x32_bf16 v[70:73], v[172:175], v[212:215], v[70:73]
	v_mfma_f32_16x16x32_bf16 v[66:69], v[180:183], v[212:215], v[66:69]
	v_mfma_f32_16x16x32_bf16 v[118:121], v[176:179], v[192:195], v[118:121]
	v_mfma_f32_16x16x32_bf16 v[114:117], v[184:187], v[192:195], v[114:117]
	v_mfma_f32_16x16x32_bf16 v[102:105], v[176:179], v[200:203], v[102:105]
	v_mfma_f32_16x16x32_bf16 v[98:101], v[184:187], v[200:203], v[98:101]
	v_mfma_f32_16x16x32_bf16 v[86:89], v[176:179], v[208:211], v[86:89]
	v_mfma_f32_16x16x32_bf16 v[82:85], v[184:187], v[208:211], v[82:85]
	v_mfma_f32_16x16x32_bf16 v[70:73], v[176:179], v[216:219], v[70:73]
	v_mfma_f32_16x16x32_bf16 v[66:69], v[184:187], v[216:219], v[66:69]
	s_barrier
	s_add_i32 s24, s62, s21
	v_lshl_add_u64 v[146:147], v[146:147], 0, s[8:9]
	s_mov_b32 m0, s24
	ds_read_b128 v[188:191], v152 offset:49152
	ds_read_b128 v[192:195], v152 offset:50176
	ds_read_b128 v[196:199], v152 offset:51200
	ds_read_b128 v[200:203], v152 offset:52224
	ds_read_b128 v[204:207], v152 offset:53248
	ds_read_b128 v[208:211], v152 offset:54272
	ds_read_b128 v[212:215], v152 offset:55296
	ds_read_b128 v[216:219], v152 offset:56320
	global_load_lds_dwordx4 v[146:147], off
	s_add_i32 m0, s24, 0x2000
	s_add_u32 s24, s42, 0x80080
	v_lshl_add_u64 v[146:147], v[220:221], 0, s[8:9]
	s_addc_u32 s25, s43, 0
	s_add_i32 s42, s63, s21
	global_load_lds_dwordx4 v[146:147], off
	v_lshl_add_u64 v[146:147], s[24:25], 0, v[132:133]
	s_mov_b32 m0, s42
	s_nop 0
	global_load_lds_dwordx4 v[146:147], off
	v_lshl_add_u64 v[146:147], s[24:25], 0, v[136:137]
	s_add_i32 m0, s42, 0x2000
	s_nop 0
	global_load_lds_dwordx4 v[146:147], off
	v_lshl_add_u64 v[146:147], v[222:223], 0, s[8:9]
	s_mov_b32 m0, s50
	s_nop 0
	global_load_lds_dwordx4 v[146:147], off
	v_lshl_add_u64 v[146:147], v[224:225], 0, s[8:9]
	s_mov_b32 m0, s51
	s_nop 0
	global_load_lds_dwordx4 v[146:147], off
	s_waitcnt vmcnt(8)
	s_waitcnt lgkmcnt(0)
	s_barrier
	s_waitcnt lgkmcnt(0)
	v_mfma_f32_16x16x32_bf16 v[62:65], v[154:157], v[188:191], v[62:65]
	v_mfma_f32_16x16x32_bf16 v[58:61], v[164:167], v[188:191], v[58:61]
	v_mfma_f32_16x16x32_bf16 v[46:49], v[154:157], v[196:199], v[46:49]
	v_mfma_f32_16x16x32_bf16 v[42:45], v[164:167], v[196:199], v[42:45]
	v_mfma_f32_16x16x32_bf16 v[30:33], v[154:157], v[204:207], v[30:33]
	v_mfma_f32_16x16x32_bf16 v[26:29], v[164:167], v[204:207], v[26:29]
	v_mfma_f32_16x16x32_bf16 v[14:17], v[154:157], v[212:215], v[14:17]
	v_mfma_f32_16x16x32_bf16 v[10:13], v[164:167], v[212:215], v[10:13]
	v_mfma_f32_16x16x32_bf16 v[62:65], v[158:161], v[192:195], v[62:65]
	v_mfma_f32_16x16x32_bf16 v[58:61], v[168:171], v[192:195], v[58:61]
	v_mfma_f32_16x16x32_bf16 v[46:49], v[158:161], v[200:203], v[46:49]
	v_mfma_f32_16x16x32_bf16 v[42:45], v[168:171], v[200:203], v[42:45]
	v_mfma_f32_16x16x32_bf16 v[30:33], v[158:161], v[208:211], v[30:33]
	v_mfma_f32_16x16x32_bf16 v[26:29], v[168:171], v[208:211], v[26:29]
	v_mfma_f32_16x16x32_bf16 v[14:17], v[158:161], v[216:219], v[14:17]
	v_mfma_f32_16x16x32_bf16 v[10:13], v[168:171], v[216:219], v[10:13]
	v_mfma_f32_16x16x32_bf16 v[54:57], v[172:175], v[188:191], v[54:57]
	v_mfma_f32_16x16x32_bf16 v[50:53], v[180:183], v[188:191], v[50:53]
	v_mfma_f32_16x16x32_bf16 v[38:41], v[172:175], v[196:199], v[38:41]
	v_mfma_f32_16x16x32_bf16 v[34:37], v[180:183], v[196:199], v[34:37]
	v_mfma_f32_16x16x32_bf16 v[22:25], v[172:175], v[204:207], v[22:25]
	v_mfma_f32_16x16x32_bf16 v[18:21], v[180:183], v[204:207], v[18:21]
	v_mfma_f32_16x16x32_bf16 v[6:9], v[172:175], v[212:215], v[6:9]
	v_mfma_f32_16x16x32_bf16 v[2:5], v[180:183], v[212:215], v[2:5]
	v_mfma_f32_16x16x32_bf16 v[54:57], v[176:179], v[192:195], v[54:57]
	v_mfma_f32_16x16x32_bf16 v[50:53], v[184:187], v[192:195], v[50:53]
	v_mfma_f32_16x16x32_bf16 v[38:41], v[176:179], v[200:203], v[38:41]
	v_mfma_f32_16x16x32_bf16 v[34:37], v[184:187], v[200:203], v[34:37]
	v_mfma_f32_16x16x32_bf16 v[22:25], v[176:179], v[208:211], v[22:25]
	v_mfma_f32_16x16x32_bf16 v[18:21], v[184:187], v[208:211], v[18:21]
	v_mfma_f32_16x16x32_bf16 v[6:9], v[176:179], v[216:219], v[6:9]
	v_mfma_f32_16x16x32_bf16 v[2:5], v[184:187], v[216:219], v[2:5]
	s_barrier
	s_add_i32 s61, s61, 2
	s_add_u32 s40, s40, 0x100
	s_addc_u32 s41, s41, 0
	s_add_u32 s59, s59, 0x100
	s_addc_u32 s60, s60, 0
	s_cmp_gt_u32 s61, 29
	s_cbranch_scc0 .LBB0_327
	s_and_b64 vcc, exec, s[10:11]
	s_cbranch_vccz .LBB0_330
	s_barrier

.LBB0_424:
	ds_read_b128 v[150:153], v163
	ds_read_b128 v[154:157], v163 offset:1024
	ds_read_b128 v[166:169], v163 offset:2048
	ds_read_b128 v[170:173], v163 offset:3072
	ds_read_b128 v[174:177], v164
	ds_read_b128 v[178:181], v164 offset:1024
	ds_read_b128 v[182:185], v164 offset:2048
	ds_read_b128 v[186:189], v164 offset:3072
	s_add_i32 s25, s24, 2
	s_add_u32 s48, s6, 0xffea0080
	s_addc_u32 s49, s7, -1
	s_cmp_eq_u32 s78, s24
	s_cselect_b32 s51, s74, s49
	s_cselect_b32 s50, s75, s48
	s_cselect_b32 s49, s76, s80
	s_cselect_b32 s48, s77, s79
	s_cselect_b64 s[100:101], s[42:43], -1
	v_lshl_add_u64 v[158:159], s[6:7], 0, v[142:143]
	s_add_i32 m0, s53, 0xc000
	ds_read_b128 v[190:193], v165
	ds_read_b128 v[194:197], v165 offset:1024
	ds_read_b128 v[198:201], v165 offset:2048
	ds_read_b128 v[202:205], v165 offset:3072
	ds_read_b128 v[206:209], v165 offset:4096
	ds_read_b128 v[210:213], v165 offset:5120
	ds_read_b128 v[214:217], v165 offset:6144
	ds_read_b128 v[218:221], v165 offset:7168
	global_load_lds_dwordx4 v[158:159], off
	v_lshl_add_u64 v[158:159], s[6:7], 0, v[144:145]
	s_add_i32 m0, s53, 0xe000
	s_nop 0
	global_load_lds_dwordx4 v[158:159], off
	s_waitcnt vmcnt(8)
	s_waitcnt lgkmcnt(0)
	s_barrier
	s_waitcnt lgkmcnt(0)
	v_mfma_f32_16x16x32_bf16 v[86:89], v[150:153], v[190:193], v[86:89]
	v_mfma_f32_16x16x32_bf16 v[78:81], v[166:169], v[190:193], v[78:81]
	v_mfma_f32_16x16x32_bf16 v[66:69], v[150:153], v[198:201], v[66:69]
	v_mfma_f32_16x16x32_bf16 v[62:65], v[166:169], v[198:201], v[62:65]
	v_mfma_f32_16x16x32_bf16 v[54:57], v[150:153], v[206:209], v[54:57]
	v_mfma_f32_16x16x32_bf16 v[46:49], v[166:169], v[206:209], v[46:49]
	v_mfma_f32_16x16x32_bf16 v[38:41], v[150:153], v[214:217], v[38:41]
	v_mfma_f32_16x16x32_bf16 v[30:33], v[166:169], v[214:217], v[30:33]
	v_mfma_f32_16x16x32_bf16 v[86:89], v[154:157], v[194:197], v[86:89]
	v_mfma_f32_16x16x32_bf16 v[78:81], v[170:173], v[194:197], v[78:81]
	v_mfma_f32_16x16x32_bf16 v[66:69], v[154:157], v[202:205], v[66:69]
	v_mfma_f32_16x16x32_bf16 v[62:65], v[170:173], v[202:205], v[62:65]
	v_mfma_f32_16x16x32_bf16 v[54:57], v[154:157], v[210:213], v[54:57]
	v_mfma_f32_16x16x32_bf16 v[46:49], v[170:173], v[210:213], v[46:49]
	v_mfma_f32_16x16x32_bf16 v[38:41], v[154:157], v[218:221], v[38:41]
	v_mfma_f32_16x16x32_bf16 v[30:33], v[170:173], v[218:221], v[30:33]
	v_mfma_f32_16x16x32_bf16 v[50:53], v[174:177], v[190:193], v[50:53]
	v_mfma_f32_16x16x32_bf16 v[42:45], v[182:185], v[190:193], v[42:45]
	v_mfma_f32_16x16x32_bf16 v[34:37], v[174:177], v[198:201], v[34:37]
	v_mfma_f32_16x16x32_bf16 v[26:29], v[182:185], v[198:201], v[26:29]
	v_mfma_f32_16x16x32_bf16 v[22:25], v[174:177], v[206:209], v[22:25]
	v_mfma_f32_16x16x32_bf16 v[18:21], v[182:185], v[206:209], v[18:21]
	v_mfma_f32_16x16x32_bf16 v[10:13], v[174:177], v[214:217], v[10:13]
	v_mfma_f32_16x16x32_bf16 v[6:9], v[182:185], v[214:217], v[6:9]
	v_mfma_f32_16x16x32_bf16 v[50:53], v[178:181], v[194:197], v[50:53]
	v_mfma_f32_16x16x32_bf16 v[42:45], v[186:189], v[194:197], v[42:45]
	v_mfma_f32_16x16x32_bf16 v[34:37], v[178:181], v[202:205], v[34:37]
	v_mfma_f32_16x16x32_bf16 v[26:29], v[186:189], v[202:205], v[26:29]
	v_mfma_f32_16x16x32_bf16 v[22:25], v[178:181], v[210:213], v[22:25]
	v_mfma_f32_16x16x32_bf16 v[18:21], v[186:189], v[210:213], v[18:21]
	v_mfma_f32_16x16x32_bf16 v[10:13], v[178:181], v[218:221], v[10:13]
	v_mfma_f32_16x16x32_bf16 v[6:9], v[186:189], v[218:221], v[6:9]
	s_barrier
	s_add_i32 s24, s66, s52
	v_lshl_add_u64 v[158:159], s[48:49], 0, v[132:133]
	s_mov_b32 m0, s24
	ds_read_b128 v[190:193], v165 offset:16384
	ds_read_b128 v[194:197], v165 offset:17408
	ds_read_b128 v[198:201], v165 offset:18432
	ds_read_b128 v[202:205], v165 offset:19456
	ds_read_b128 v[206:209], v165 offset:20480
	ds_read_b128 v[210:213], v165 offset:21504
	ds_read_b128 v[214:217], v165 offset:22528
	ds_read_b128 v[218:221], v165 offset:23552
	global_load_lds_dwordx4 v[158:159], off
	s_add_i32 m0, s24, 0x2000
	s_add_u32 s82, s48, 0x160000
	v_lshl_add_u64 v[222:223], s[48:49], 0, v[136:137]
	s_addc_u32 s83, s49, 0
	s_add_i32 s24, s67, s52
	global_load_lds_dwordx4 v[222:223], off
	v_lshl_add_u64 v[224:225], s[82:83], 0, v[132:133]
	s_mov_b32 m0, s24
	v_lshl_add_u64 v[226:227], s[50:51], 0, v[134:135]
	global_load_lds_dwordx4 v[224:225], off
	v_lshl_add_u64 v[224:225], s[82:83], 0, v[136:137]
	s_add_i32 m0, s24, 0x2000
	s_nop 0
	global_load_lds_dwordx4 v[224:225], off
	v_lshl_add_u64 v[224:225], s[50:51], 0, v[130:131]
	s_mov_b32 m0, s53
	s_nop 0
	global_load_lds_dwordx4 v[224:225], off
	s_mov_b32 m0, s54
	s_nop 0
	global_load_lds_dwordx4 v[226:227], off
	s_waitcnt vmcnt(8)
	s_waitcnt lgkmcnt(0)
	s_barrier
	s_waitcnt lgkmcnt(0)
	v_mfma_f32_16x16x32_bf16 v[126:129], v[150:153], v[190:193], v[126:129]
	v_mfma_f32_16x16x32_bf16 v[122:125], v[166:169], v[190:193], v[122:125]
	v_mfma_f32_16x16x32_bf16 v[110:113], v[150:153], v[198:201], v[110:113]
	v_mfma_f32_16x16x32_bf16 v[106:109], v[166:169], v[198:201], v[106:109]
	v_mfma_f32_16x16x32_bf16 v[94:97], v[150:153], v[206:209], v[94:97]
	v_mfma_f32_16x16x32_bf16 v[90:93], v[166:169], v[206:209], v[90:93]
	v_mfma_f32_16x16x32_bf16 v[70:73], v[150:153], v[214:217], v[70:73]
	v_mfma_f32_16x16x32_bf16 v[58:61], v[166:169], v[214:217], v[58:61]
	v_mfma_f32_16x16x32_bf16 v[126:129], v[154:157], v[194:197], v[126:129]
	v_mfma_f32_16x16x32_bf16 v[122:125], v[170:173], v[194:197], v[122:125]
	v_mfma_f32_16x16x32_bf16 v[110:113], v[154:157], v[202:205], v[110:113]
	v_mfma_f32_16x16x32_bf16 v[106:109], v[170:173], v[202:205], v[106:109]
	v_mfma_f32_16x16x32_bf16 v[94:97], v[154:157], v[210:213], v[94:97]
	v_mfma_f32_16x16x32_bf16 v[90:93], v[170:173], v[210:213], v[90:93]
	v_mfma_f32_16x16x32_bf16 v[70:73], v[154:157], v[218:221], v[70:73]
	v_mfma_f32_16x16x32_bf16 v[58:61], v[170:173], v[218:221], v[58:61]
	v_mfma_f32_16x16x32_bf16 v[118:121], v[174:177], v[190:193], v[118:121]
	v_mfma_f32_16x16x32_bf16 v[114:117], v[182:185], v[190:193], v[114:117]
	v_mfma_f32_16x16x32_bf16 v[102:105], v[174:177], v[198:201], v[102:105]
	v_mfma_f32_16x16x32_bf16 v[98:101], v[182:185], v[198:201], v[98:101]
	v_mfma_f32_16x16x32_bf16 v[82:85], v[174:177], v[206:209], v[82:85]
	v_mfma_f32_16x16x32_bf16 v[74:77], v[182:185], v[206:209], v[74:77]
	v_mfma_f32_16x16x32_bf16 v[14:17], v[174:177], v[214:217], v[14:17]
	v_mfma_f32_16x16x32_bf16 v[2:5], v[182:185], v[214:217], v[2:5]
	v_mfma_f32_16x16x32_bf16 v[118:121], v[178:181], v[194:197], v[118:121]
	v_mfma_f32_16x16x32_bf16 v[114:117], v[186:189], v[194:197], v[114:117]
	v_mfma_f32_16x16x32_bf16 v[102:105], v[178:181], v[202:205], v[102:105]
	v_mfma_f32_16x16x32_bf16 v[98:101], v[186:189], v[202:205], v[98:101]
	v_mfma_f32_16x16x32_bf16 v[82:85], v[178:181], v[210:213], v[82:85]
	v_mfma_f32_16x16x32_bf16 v[74:77], v[186:189], v[210:213], v[74:77]
	v_mfma_f32_16x16x32_bf16 v[14:17], v[178:181], v[218:221], v[14:17]
	v_mfma_f32_16x16x32_bf16 v[2:5], v[186:189], v[218:221], v[2:5]
	s_barrier
	s_add_i32 s24, 0, 0x18000
	v_add_u32_e32 v138, s24, v160
	s_add_i32 s81, 0, 0x1c000
	ds_read_b128 v[150:153], v138
	ds_read_b128 v[154:157], v138 offset:1024
	ds_read_b128 v[166:169], v138 offset:2048
	ds_read_b128 v[170:173], v138 offset:3072
	v_add_u32_e32 v138, s81, v160
	ds_read_b128 v[174:177], v138
	ds_read_b128 v[178:181], v138 offset:1024
	ds_read_b128 v[182:185], v138 offset:2048
	ds_read_b128 v[186:189], v138 offset:3072
	s_add_u32 s50, s50, 0x160000
	s_addc_u32 s51, s51, 0
	s_mov_b32 m0, s55
	v_lshl_add_u64 v[228:229], s[50:51], 0, v[130:131]
	ds_read_b128 v[190:193], v165 offset:32768
	ds_read_b128 v[194:197], v165 offset:33792
	ds_read_b128 v[198:201], v165 offset:34816
	ds_read_b128 v[202:205], v165 offset:35840
	ds_read_b128 v[206:209], v165 offset:36864
	ds_read_b128 v[210:213], v165 offset:37888
	ds_read_b128 v[214:217], v165 offset:38912
	ds_read_b128 v[218:221], v165 offset:39936
	s_mov_b64 exec, s[100:101]
	global_load_lds_dwordx4 v[228:229], off
	s_mov_b64 exec, -1
	v_lshl_add_u64 v[228:229], s[50:51], 0, v[134:135]
	s_mov_b32 m0, s56
	s_nop 0
	s_mov_b64 exec, s[100:101]
	global_load_lds_dwordx4 v[228:229], off
	s_mov_b64 exec, -1
	s_waitcnt vmcnt(8)
	s_waitcnt lgkmcnt(0)
	s_barrier
	s_waitcnt lgkmcnt(0)
	v_mfma_f32_16x16x32_bf16 v[86:89], v[150:153], v[190:193], v[86:89]
	v_mfma_f32_16x16x32_bf16 v[78:81], v[166:169], v[190:193], v[78:81]
	v_mfma_f32_16x16x32_bf16 v[66:69], v[150:153], v[198:201], v[66:69]
	v_mfma_f32_16x16x32_bf16 v[62:65], v[166:169], v[198:201], v[62:65]
	v_mfma_f32_16x16x32_bf16 v[54:57], v[150:153], v[206:209], v[54:57]
	v_mfma_f32_16x16x32_bf16 v[46:49], v[166:169], v[206:209], v[46:49]
	v_mfma_f32_16x16x32_bf16 v[38:41], v[150:153], v[214:217], v[38:41]
	v_mfma_f32_16x16x32_bf16 v[30:33], v[166:169], v[214:217], v[30:33]
	v_mfma_f32_16x16x32_bf16 v[86:89], v[154:157], v[194:197], v[86:89]
	v_mfma_f32_16x16x32_bf16 v[78:81], v[170:173], v[194:197], v[78:81]
	v_mfma_f32_16x16x32_bf16 v[66:69], v[154:157], v[202:205], v[66:69]
	v_mfma_f32_16x16x32_bf16 v[62:65], v[170:173], v[202:205], v[62:65]
	v_mfma_f32_16x16x32_bf16 v[54:57], v[154:157], v[210:213], v[54:57]
	v_mfma_f32_16x16x32_bf16 v[46:49], v[170:173], v[210:213], v[46:49]
	v_mfma_f32_16x16x32_bf16 v[38:41], v[154:157], v[218:221], v[38:41]
	v_mfma_f32_16x16x32_bf16 v[30:33], v[170:173], v[218:221], v[30:33]
	v_mfma_f32_16x16x32_bf16 v[50:53], v[174:177], v[190:193], v[50:53]
	v_mfma_f32_16x16x32_bf16 v[42:45], v[182:185], v[190:193], v[42:45]
	v_mfma_f32_16x16x32_bf16 v[34:37], v[174:177], v[198:201], v[34:37]
	v_mfma_f32_16x16x32_bf16 v[26:29], v[182:185], v[198:201], v[26:29]
	v_mfma_f32_16x16x32_bf16 v[22:25], v[174:177], v[206:209], v[22:25]
	v_mfma_f32_16x16x32_bf16 v[18:21], v[182:185], v[206:209], v[18:21]
	v_mfma_f32_16x16x32_bf16 v[10:13], v[174:177], v[214:217], v[10:13]
	v_mfma_f32_16x16x32_bf16 v[6:9], v[182:185], v[214:217], v[6:9]
	v_mfma_f32_16x16x32_bf16 v[50:53], v[178:181], v[194:197], v[50:53]
	v_mfma_f32_16x16x32_bf16 v[42:45], v[186:189], v[194:197], v[42:45]
	v_mfma_f32_16x16x32_bf16 v[34:37], v[178:181], v[202:205], v[34:37]
	v_mfma_f32_16x16x32_bf16 v[26:29], v[186:189], v[202:205], v[26:29]
	v_mfma_f32_16x16x32_bf16 v[22:25], v[178:181], v[210:213], v[22:25]
	v_mfma_f32_16x16x32_bf16 v[18:21], v[186:189], v[210:213], v[18:21]
	v_mfma_f32_16x16x32_bf16 v[10:13], v[178:181], v[218:221], v[10:13]
	v_mfma_f32_16x16x32_bf16 v[6:9], v[186:189], v[218:221], v[6:9]
	s_barrier
	s_add_i32 s24, s24, s52
	v_lshl_add_u64 v[158:159], v[158:159], 0, s[14:15]
	s_mov_b32 m0, s24
	ds_read_b128 v[190:193], v165 offset:49152
	ds_read_b128 v[194:197], v165 offset:50176
	ds_read_b128 v[198:201], v165 offset:51200
	ds_read_b128 v[202:205], v165 offset:52224
	ds_read_b128 v[206:209], v165 offset:53248
	ds_read_b128 v[210:213], v165 offset:54272
	ds_read_b128 v[214:217], v165 offset:55296
	ds_read_b128 v[218:221], v165 offset:56320
	s_mov_b64 exec, s[100:101]
	global_load_lds_dwordx4 v[158:159], off
	s_mov_b64 exec, -1
	s_add_i32 m0, s24, 0x2000
	s_add_u32 s48, s48, 0x160080
	v_lshl_add_u64 v[158:159], v[222:223], 0, s[14:15]
	s_addc_u32 s49, s49, 0
	s_add_i32 s24, s81, s52
	s_mov_b64 exec, s[100:101]
	global_load_lds_dwordx4 v[158:159], off
	s_mov_b64 exec, -1
	v_lshl_add_u64 v[158:159], s[48:49], 0, v[132:133]
	s_mov_b32 m0, s24
	s_nop 0
	s_mov_b64 exec, s[100:101]
	global_load_lds_dwordx4 v[158:159], off
	s_mov_b64 exec, -1
	v_lshl_add_u64 v[158:159], s[48:49], 0, v[136:137]
	s_add_i32 m0, s24, 0x2000
	s_nop 0
	s_mov_b64 exec, s[100:101]
	global_load_lds_dwordx4 v[158:159], off
	s_mov_b64 exec, -1
	v_lshl_add_u64 v[158:159], v[224:225], 0, s[14:15]
	s_mov_b32 m0, s62
	s_nop 0
	s_mov_b64 exec, s[100:101]
	global_load_lds_dwordx4 v[158:159], off
	s_mov_b64 exec, -1
	v_lshl_add_u64 v[158:159], v[226:227], 0, s[14:15]
	s_mov_b32 m0, s63
	s_nop 0
	s_mov_b64 exec, s[100:101]
	global_load_lds_dwordx4 v[158:159], off
	s_mov_b64 exec, -1
	s_waitcnt vmcnt(8)
	s_waitcnt lgkmcnt(0)
	s_barrier
	s_waitcnt lgkmcnt(0)
	v_mfma_f32_16x16x32_bf16 v[126:129], v[150:153], v[190:193], v[126:129]
	v_mfma_f32_16x16x32_bf16 v[122:125], v[166:169], v[190:193], v[122:125]
	v_mfma_f32_16x16x32_bf16 v[110:113], v[150:153], v[198:201], v[110:113]
	v_mfma_f32_16x16x32_bf16 v[106:109], v[166:169], v[198:201], v[106:109]
	v_mfma_f32_16x16x32_bf16 v[94:97], v[150:153], v[206:209], v[94:97]
	v_mfma_f32_16x16x32_bf16 v[90:93], v[166:169], v[206:209], v[90:93]
	v_mfma_f32_16x16x32_bf16 v[70:73], v[150:153], v[214:217], v[70:73]
	v_mfma_f32_16x16x32_bf16 v[58:61], v[166:169], v[214:217], v[58:61]
	v_mfma_f32_16x16x32_bf16 v[126:129], v[154:157], v[194:197], v[126:129]
	v_mfma_f32_16x16x32_bf16 v[122:125], v[170:173], v[194:197], v[122:125]
	v_mfma_f32_16x16x32_bf16 v[110:113], v[154:157], v[202:205], v[110:113]
	v_mfma_f32_16x16x32_bf16 v[106:109], v[170:173], v[202:205], v[106:109]
	v_mfma_f32_16x16x32_bf16 v[94:97], v[154:157], v[210:213], v[94:97]
	v_mfma_f32_16x16x32_bf16 v[90:93], v[170:173], v[210:213], v[90:93]
	v_mfma_f32_16x16x32_bf16 v[70:73], v[154:157], v[218:221], v[70:73]
	v_mfma_f32_16x16x32_bf16 v[58:61], v[170:173], v[218:221], v[58:61]
	v_mfma_f32_16x16x32_bf16 v[118:121], v[174:177], v[190:193], v[118:121]
	v_mfma_f32_16x16x32_bf16 v[114:117], v[182:185], v[190:193], v[114:117]
	v_mfma_f32_16x16x32_bf16 v[102:105], v[174:177], v[198:201], v[102:105]
	v_mfma_f32_16x16x32_bf16 v[98:101], v[182:185], v[198:201], v[98:101]
	v_mfma_f32_16x16x32_bf16 v[82:85], v[174:177], v[206:209], v[82:85]
	v_mfma_f32_16x16x32_bf16 v[74:77], v[182:185], v[206:209], v[74:77]
	v_mfma_f32_16x16x32_bf16 v[14:17], v[174:177], v[214:217], v[14:17]
	v_mfma_f32_16x16x32_bf16 v[2:5], v[182:185], v[214:217], v[2:5]
	v_mfma_f32_16x16x32_bf16 v[118:121], v[178:181], v[194:197], v[118:121]
	v_mfma_f32_16x16x32_bf16 v[114:117], v[186:189], v[194:197], v[114:117]
	v_mfma_f32_16x16x32_bf16 v[102:105], v[178:181], v[202:205], v[102:105]
	v_mfma_f32_16x16x32_bf16 v[98:101], v[186:189], v[202:205], v[98:101]
	v_mfma_f32_16x16x32_bf16 v[82:85], v[178:181], v[210:213], v[82:85]
	v_mfma_f32_16x16x32_bf16 v[74:77], v[186:189], v[210:213], v[74:77]
	v_mfma_f32_16x16x32_bf16 v[14:17], v[178:181], v[218:221], v[14:17]
	v_mfma_f32_16x16x32_bf16 v[2:5], v[186:189], v[218:221], v[2:5]
	s_barrier
	s_add_u32 s6, s6, 0x100
	s_addc_u32 s7, s7, 0
	s_add_u32 s79, s79, 0x100
	s_addc_u32 s80, s80, 0
	s_cmp_ge_i32 s25, s73
	s_mov_b32 s24, s25
	s_cbranch_scc0 .LBB0_424
	s_and_b64 vcc, exec, s[16:17]
	s_cbranch_vccz .LBB0_427
	s_barrier

.LBB0_587:
	ds_read_b128 v[156:159], v152
	ds_read_b128 v[164:167], v152 offset:1024
	ds_read_b128 v[168:171], v152 offset:2048
	ds_read_b128 v[172:175], v152 offset:3072
	ds_read_b128 v[176:179], v153
	ds_read_b128 v[180:183], v153 offset:1024
	ds_read_b128 v[184:187], v153 offset:2048
	ds_read_b128 v[188:191], v153 offset:3072
	s_add_i32 s25, s24, 2
	s_add_u32 s58, s56, 0xfff80080
	s_addc_u32 s59, s57, -1
	s_cmp_eq_u32 s82, s24
	s_cselect_b32 s61, s39, s59
	s_cselect_b32 s60, s49, s58
	s_cselect_b32 s59, s80, s84
	s_cselect_b32 s58, s81, s83
	s_cselect_b64 s[100:101], s[50:51], -1
	v_lshl_add_u64 v[150:151], s[56:57], 0, v[142:143]
	s_add_i32 m0, s62, 0xc000
	ds_read_b128 v[192:195], v154
	ds_read_b128 v[196:199], v154 offset:1024
	ds_read_b128 v[200:203], v154 offset:2048
	ds_read_b128 v[204:207], v154 offset:3072
	ds_read_b128 v[208:211], v154 offset:4096
	ds_read_b128 v[212:215], v154 offset:5120
	ds_read_b128 v[216:219], v154 offset:6144
	ds_read_b128 v[220:223], v154 offset:7168
	global_load_lds_dwordx4 v[150:151], off
	v_lshl_add_u64 v[150:151], s[56:57], 0, v[144:145]
	s_add_i32 m0, s62, 0xe000
	s_nop 0
	global_load_lds_dwordx4 v[150:151], off
	s_waitcnt vmcnt(8)
	s_waitcnt lgkmcnt(0)
	s_barrier
	s_waitcnt lgkmcnt(0)
	v_mfma_f32_16x16x32_bf16 v[106:109], v[156:159], v[192:195], v[106:109]
	v_mfma_f32_16x16x32_bf16 v[98:101], v[168:171], v[192:195], v[98:101]
	v_mfma_f32_16x16x32_bf16 v[90:93], v[156:159], v[200:203], v[90:93]
	v_mfma_f32_16x16x32_bf16 v[82:85], v[168:171], v[200:203], v[82:85]
	v_mfma_f32_16x16x32_bf16 v[70:73], v[156:159], v[208:211], v[70:73]
	v_mfma_f32_16x16x32_bf16 v[62:65], v[168:171], v[208:211], v[62:65]
	v_mfma_f32_16x16x32_bf16 v[46:49], v[156:159], v[216:219], v[46:49]
	v_mfma_f32_16x16x32_bf16 v[38:41], v[168:171], v[216:219], v[38:41]
	v_mfma_f32_16x16x32_bf16 v[106:109], v[164:167], v[196:199], v[106:109]
	v_mfma_f32_16x16x32_bf16 v[98:101], v[172:175], v[196:199], v[98:101]
	v_mfma_f32_16x16x32_bf16 v[90:93], v[164:167], v[204:207], v[90:93]
	v_mfma_f32_16x16x32_bf16 v[82:85], v[172:175], v[204:207], v[82:85]
	v_mfma_f32_16x16x32_bf16 v[70:73], v[164:167], v[212:215], v[70:73]
	v_mfma_f32_16x16x32_bf16 v[62:65], v[172:175], v[212:215], v[62:65]
	v_mfma_f32_16x16x32_bf16 v[46:49], v[164:167], v[220:223], v[46:49]
	v_mfma_f32_16x16x32_bf16 v[38:41], v[172:175], v[220:223], v[38:41]
	v_mfma_f32_16x16x32_bf16 v[66:69], v[176:179], v[192:195], v[66:69]
	v_mfma_f32_16x16x32_bf16 v[58:61], v[184:187], v[192:195], v[58:61]
	v_mfma_f32_16x16x32_bf16 v[42:45], v[176:179], v[200:203], v[42:45]
	v_mfma_f32_16x16x32_bf16 v[34:37], v[184:187], v[200:203], v[34:37]
	v_mfma_f32_16x16x32_bf16 v[22:25], v[176:179], v[208:211], v[22:25]
	v_mfma_f32_16x16x32_bf16 v[18:21], v[184:187], v[208:211], v[18:21]
	v_mfma_f32_16x16x32_bf16 v[14:17], v[176:179], v[216:219], v[14:17]
	v_mfma_f32_16x16x32_bf16 v[6:9], v[184:187], v[216:219], v[6:9]
	v_mfma_f32_16x16x32_bf16 v[66:69], v[180:183], v[196:199], v[66:69]
	v_mfma_f32_16x16x32_bf16 v[58:61], v[188:191], v[196:199], v[58:61]
	v_mfma_f32_16x16x32_bf16 v[42:45], v[180:183], v[204:207], v[42:45]
	v_mfma_f32_16x16x32_bf16 v[34:37], v[188:191], v[204:207], v[34:37]
	v_mfma_f32_16x16x32_bf16 v[22:25], v[180:183], v[212:215], v[22:25]
	v_mfma_f32_16x16x32_bf16 v[18:21], v[188:191], v[212:215], v[18:21]
	v_mfma_f32_16x16x32_bf16 v[14:17], v[180:183], v[220:223], v[14:17]
	v_mfma_f32_16x16x32_bf16 v[6:9], v[188:191], v[220:223], v[6:9]
	s_barrier
	s_add_i32 s24, s72, s31
	v_lshl_add_u64 v[150:151], s[58:59], 0, v[132:133]
	s_mov_b32 m0, s24
	ds_read_b128 v[192:195], v154 offset:16384
	ds_read_b128 v[196:199], v154 offset:17408
	ds_read_b128 v[200:203], v154 offset:18432
	ds_read_b128 v[204:207], v154 offset:19456
	ds_read_b128 v[208:211], v154 offset:20480
	ds_read_b128 v[212:215], v154 offset:21504
	ds_read_b128 v[216:219], v154 offset:22528
	ds_read_b128 v[220:223], v154 offset:23552
	global_load_lds_dwordx4 v[150:151], off
	s_add_i32 m0, s24, 0x2000
	s_add_u32 s86, s58, 0x80000
	v_lshl_add_u64 v[160:161], s[58:59], 0, v[136:137]
	s_addc_u32 s87, s59, 0
	s_add_i32 s24, s73, s31
	global_load_lds_dwordx4 v[160:161], off
	v_lshl_add_u64 v[224:225], s[86:87], 0, v[132:133]
	s_mov_b32 m0, s24
	v_lshl_add_u64 v[226:227], s[60:61], 0, v[134:135]
	global_load_lds_dwordx4 v[224:225], off
	v_lshl_add_u64 v[224:225], s[86:87], 0, v[136:137]
	s_add_i32 m0, s24, 0x2000
	s_nop 0
	global_load_lds_dwordx4 v[224:225], off
	v_lshl_add_u64 v[224:225], s[60:61], 0, v[130:131]
	s_mov_b32 m0, s62
	s_nop 0
	global_load_lds_dwordx4 v[224:225], off
	s_mov_b32 m0, s63
	s_nop 0
	global_load_lds_dwordx4 v[226:227], off
	s_waitcnt vmcnt(8)
	s_waitcnt lgkmcnt(0)
	s_barrier
	s_waitcnt lgkmcnt(0)
	v_mfma_f32_16x16x32_bf16 v[126:129], v[156:159], v[192:195], v[126:129]
	v_mfma_f32_16x16x32_bf16 v[122:125], v[168:171], v[192:195], v[122:125]
	v_mfma_f32_16x16x32_bf16 v[118:121], v[156:159], v[200:203], v[118:121]
	v_mfma_f32_16x16x32_bf16 v[114:117], v[168:171], v[200:203], v[114:117]
	v_mfma_f32_16x16x32_bf16 v[94:97], v[156:159], v[208:211], v[94:97]
	v_mfma_f32_16x16x32_bf16 v[86:89], v[168:171], v[208:211], v[86:89]
	v_mfma_f32_16x16x32_bf16 v[54:57], v[156:159], v[216:219], v[54:57]
	v_mfma_f32_16x16x32_bf16 v[50:53], v[168:171], v[216:219], v[50:53]
	v_mfma_f32_16x16x32_bf16 v[126:129], v[164:167], v[196:199], v[126:129]
	v_mfma_f32_16x16x32_bf16 v[122:125], v[172:175], v[196:199], v[122:125]
	v_mfma_f32_16x16x32_bf16 v[118:121], v[164:167], v[204:207], v[118:121]
	v_mfma_f32_16x16x32_bf16 v[114:117], v[172:175], v[204:207], v[114:117]
	v_mfma_f32_16x16x32_bf16 v[94:97], v[164:167], v[212:215], v[94:97]
	v_mfma_f32_16x16x32_bf16 v[86:89], v[172:175], v[212:215], v[86:89]
	v_mfma_f32_16x16x32_bf16 v[54:57], v[164:167], v[220:223], v[54:57]
	v_mfma_f32_16x16x32_bf16 v[50:53], v[172:175], v[220:223], v[50:53]
	v_mfma_f32_16x16x32_bf16 v[110:113], v[176:179], v[192:195], v[110:113]
	v_mfma_f32_16x16x32_bf16 v[102:105], v[184:187], v[192:195], v[102:105]
	v_mfma_f32_16x16x32_bf16 v[78:81], v[176:179], v[200:203], v[78:81]
	v_mfma_f32_16x16x32_bf16 v[74:77], v[184:187], v[200:203], v[74:77]
	v_mfma_f32_16x16x32_bf16 v[30:33], v[176:179], v[208:211], v[30:33]
	v_mfma_f32_16x16x32_bf16 v[26:29], v[184:187], v[208:211], v[26:29]
	v_mfma_f32_16x16x32_bf16 v[10:13], v[176:179], v[216:219], v[10:13]
	v_mfma_f32_16x16x32_bf16 v[2:5], v[184:187], v[216:219], v[2:5]
	v_mfma_f32_16x16x32_bf16 v[110:113], v[180:183], v[196:199], v[110:113]
	v_mfma_f32_16x16x32_bf16 v[102:105], v[188:191], v[196:199], v[102:105]
	v_mfma_f32_16x16x32_bf16 v[78:81], v[180:183], v[204:207], v[78:81]
	v_mfma_f32_16x16x32_bf16 v[74:77], v[188:191], v[204:207], v[74:77]
	v_mfma_f32_16x16x32_bf16 v[30:33], v[180:183], v[212:215], v[30:33]
	v_mfma_f32_16x16x32_bf16 v[26:29], v[188:191], v[212:215], v[26:29]
	v_mfma_f32_16x16x32_bf16 v[10:13], v[180:183], v[220:223], v[10:13]
	v_mfma_f32_16x16x32_bf16 v[2:5], v[188:191], v[220:223], v[2:5]
	s_barrier
	s_add_i32 s24, 0, 0x18000
	v_add_u32_e32 v155, s24, v1
	s_add_i32 s85, 0, 0x1c000
	ds_read_b128 v[156:159], v155
	ds_read_b128 v[164:167], v155 offset:1024
	ds_read_b128 v[168:171], v155 offset:2048
	ds_read_b128 v[172:175], v155 offset:3072
	v_add_u32_e32 v155, s85, v1
	ds_read_b128 v[176:179], v155
	ds_read_b128 v[180:183], v155 offset:1024
	ds_read_b128 v[184:187], v155 offset:2048
	ds_read_b128 v[188:191], v155 offset:3072
	s_add_u32 s60, s60, 0x80000
	s_addc_u32 s61, s61, 0
	s_mov_b32 m0, s64
	v_lshl_add_u64 v[228:229], s[60:61], 0, v[130:131]
	ds_read_b128 v[192:195], v154 offset:32768
	ds_read_b128 v[196:199], v154 offset:33792
	ds_read_b128 v[200:203], v154 offset:34816
	ds_read_b128 v[204:207], v154 offset:35840
	ds_read_b128 v[208:211], v154 offset:36864
	ds_read_b128 v[212:215], v154 offset:37888
	ds_read_b128 v[216:219], v154 offset:38912
	ds_read_b128 v[220:223], v154 offset:39936
	s_mov_b64 exec, s[100:101]
	global_load_lds_dwordx4 v[228:229], off
	s_mov_b64 exec, -1
	v_lshl_add_u64 v[228:229], s[60:61], 0, v[134:135]
	s_mov_b32 m0, s65
	s_nop 0
	s_mov_b64 exec, s[100:101]
	global_load_lds_dwordx4 v[228:229], off
	s_mov_b64 exec, -1
	s_waitcnt vmcnt(8)
	s_waitcnt lgkmcnt(0)
	s_barrier
	s_waitcnt lgkmcnt(0)
	v_mfma_f32_16x16x32_bf16 v[106:109], v[156:159], v[192:195], v[106:109]
	v_mfma_f32_16x16x32_bf16 v[98:101], v[168:171], v[192:195], v[98:101]
	v_mfma_f32_16x16x32_bf16 v[90:93], v[156:159], v[200:203], v[90:93]
	v_mfma_f32_16x16x32_bf16 v[82:85], v[168:171], v[200:203], v[82:85]
	v_mfma_f32_16x16x32_bf16 v[70:73], v[156:159], v[208:211], v[70:73]
	v_mfma_f32_16x16x32_bf16 v[62:65], v[168:171], v[208:211], v[62:65]
	v_mfma_f32_16x16x32_bf16 v[46:49], v[156:159], v[216:219], v[46:49]
	v_mfma_f32_16x16x32_bf16 v[38:41], v[168:171], v[216:219], v[38:41]
	v_mfma_f32_16x16x32_bf16 v[106:109], v[164:167], v[196:199], v[106:109]
	v_mfma_f32_16x16x32_bf16 v[98:101], v[172:175], v[196:199], v[98:101]
	v_mfma_f32_16x16x32_bf16 v[90:93], v[164:167], v[204:207], v[90:93]
	v_mfma_f32_16x16x32_bf16 v[82:85], v[172:175], v[204:207], v[82:85]
	v_mfma_f32_16x16x32_bf16 v[70:73], v[164:167], v[212:215], v[70:73]
	v_mfma_f32_16x16x32_bf16 v[62:65], v[172:175], v[212:215], v[62:65]
	v_mfma_f32_16x16x32_bf16 v[46:49], v[164:167], v[220:223], v[46:49]
	v_mfma_f32_16x16x32_bf16 v[38:41], v[172:175], v[220:223], v[38:41]
	v_mfma_f32_16x16x32_bf16 v[66:69], v[176:179], v[192:195], v[66:69]
	v_mfma_f32_16x16x32_bf16 v[58:61], v[184:187], v[192:195], v[58:61]
	v_mfma_f32_16x16x32_bf16 v[42:45], v[176:179], v[200:203], v[42:45]
	v_mfma_f32_16x16x32_bf16 v[34:37], v[184:187], v[200:203], v[34:37]
	v_mfma_f32_16x16x32_bf16 v[22:25], v[176:179], v[208:211], v[22:25]
	v_mfma_f32_16x16x32_bf16 v[18:21], v[184:187], v[208:211], v[18:21]
	v_mfma_f32_16x16x32_bf16 v[14:17], v[176:179], v[216:219], v[14:17]
	v_mfma_f32_16x16x32_bf16 v[6:9], v[184:187], v[216:219], v[6:9]
	v_mfma_f32_16x16x32_bf16 v[66:69], v[180:183], v[196:199], v[66:69]
	v_mfma_f32_16x16x32_bf16 v[58:61], v[188:191], v[196:199], v[58:61]
	v_mfma_f32_16x16x32_bf16 v[42:45], v[180:183], v[204:207], v[42:45]
	v_mfma_f32_16x16x32_bf16 v[34:37], v[188:191], v[204:207], v[34:37]
	v_mfma_f32_16x16x32_bf16 v[22:25], v[180:183], v[212:215], v[22:25]
	v_mfma_f32_16x16x32_bf16 v[18:21], v[188:191], v[212:215], v[18:21]
	v_mfma_f32_16x16x32_bf16 v[14:17], v[180:183], v[220:223], v[14:17]
	v_mfma_f32_16x16x32_bf16 v[6:9], v[188:191], v[220:223], v[6:9]
	s_barrier
	s_add_i32 s24, s24, s31
	v_lshl_add_u64 v[150:151], v[150:151], 0, s[12:13]
	s_mov_b32 m0, s24
	ds_read_b128 v[192:195], v154 offset:49152
	ds_read_b128 v[196:199], v154 offset:50176
	ds_read_b128 v[200:203], v154 offset:51200
	ds_read_b128 v[204:207], v154 offset:52224
	ds_read_b128 v[208:211], v154 offset:53248
	ds_read_b128 v[212:215], v154 offset:54272
	ds_read_b128 v[216:219], v154 offset:55296
	ds_read_b128 v[220:223], v154 offset:56320
	s_mov_b64 exec, s[100:101]
	global_load_lds_dwordx4 v[150:151], off
	s_mov_b64 exec, -1
	s_add_i32 m0, s24, 0x2000
	s_add_u32 s58, s58, 0x80080
	v_lshl_add_u64 v[150:151], v[160:161], 0, s[12:13]
	s_addc_u32 s59, s59, 0
	s_add_i32 s24, s85, s31
	s_mov_b64 exec, s[100:101]
	global_load_lds_dwordx4 v[150:151], off
	s_mov_b64 exec, -1
	v_lshl_add_u64 v[150:151], s[58:59], 0, v[132:133]
	s_mov_b32 m0, s24
	s_nop 0
	s_mov_b64 exec, s[100:101]
	global_load_lds_dwordx4 v[150:151], off
	s_mov_b64 exec, -1
	v_lshl_add_u64 v[150:151], s[58:59], 0, v[136:137]
	s_add_i32 m0, s24, 0x2000
	s_nop 0
	s_mov_b64 exec, s[100:101]
	global_load_lds_dwordx4 v[150:151], off
	s_mov_b64 exec, -1
	v_lshl_add_u64 v[150:151], v[224:225], 0, s[12:13]
	s_mov_b32 m0, s67
	s_nop 0
	s_mov_b64 exec, s[100:101]
	global_load_lds_dwordx4 v[150:151], off
	s_mov_b64 exec, -1
	v_lshl_add_u64 v[150:151], v[226:227], 0, s[12:13]
	s_mov_b32 m0, s68
	s_nop 0
	s_mov_b64 exec, s[100:101]
	global_load_lds_dwordx4 v[150:151], off
	s_mov_b64 exec, -1
	s_waitcnt vmcnt(8)
	s_waitcnt lgkmcnt(0)
	s_barrier
	s_waitcnt lgkmcnt(0)
	v_mfma_f32_16x16x32_bf16 v[126:129], v[156:159], v[192:195], v[126:129]
	v_mfma_f32_16x16x32_bf16 v[122:125], v[168:171], v[192:195], v[122:125]
	v_mfma_f32_16x16x32_bf16 v[118:121], v[156:159], v[200:203], v[118:121]
	v_mfma_f32_16x16x32_bf16 v[114:117], v[168:171], v[200:203], v[114:117]
	v_mfma_f32_16x16x32_bf16 v[94:97], v[156:159], v[208:211], v[94:97]
	v_mfma_f32_16x16x32_bf16 v[86:89], v[168:171], v[208:211], v[86:89]
	v_mfma_f32_16x16x32_bf16 v[54:57], v[156:159], v[216:219], v[54:57]
	v_mfma_f32_16x16x32_bf16 v[50:53], v[168:171], v[216:219], v[50:53]
	v_mfma_f32_16x16x32_bf16 v[126:129], v[164:167], v[196:199], v[126:129]
	v_mfma_f32_16x16x32_bf16 v[122:125], v[172:175], v[196:199], v[122:125]
	v_mfma_f32_16x16x32_bf16 v[118:121], v[164:167], v[204:207], v[118:121]
	v_mfma_f32_16x16x32_bf16 v[114:117], v[172:175], v[204:207], v[114:117]
	v_mfma_f32_16x16x32_bf16 v[94:97], v[164:167], v[212:215], v[94:97]
	v_mfma_f32_16x16x32_bf16 v[86:89], v[172:175], v[212:215], v[86:89]
	v_mfma_f32_16x16x32_bf16 v[54:57], v[164:167], v[220:223], v[54:57]
	v_mfma_f32_16x16x32_bf16 v[50:53], v[172:175], v[220:223], v[50:53]
	v_mfma_f32_16x16x32_bf16 v[110:113], v[176:179], v[192:195], v[110:113]
	v_mfma_f32_16x16x32_bf16 v[102:105], v[184:187], v[192:195], v[102:105]
	v_mfma_f32_16x16x32_bf16 v[78:81], v[176:179], v[200:203], v[78:81]
	v_mfma_f32_16x16x32_bf16 v[74:77], v[184:187], v[200:203], v[74:77]
	v_mfma_f32_16x16x32_bf16 v[30:33], v[176:179], v[208:211], v[30:33]
	v_mfma_f32_16x16x32_bf16 v[26:29], v[184:187], v[208:211], v[26:29]
	v_mfma_f32_16x16x32_bf16 v[10:13], v[176:179], v[216:219], v[10:13]
	v_mfma_f32_16x16x32_bf16 v[2:5], v[184:187], v[216:219], v[2:5]
	v_mfma_f32_16x16x32_bf16 v[110:113], v[180:183], v[196:199], v[110:113]
	v_mfma_f32_16x16x32_bf16 v[102:105], v[188:191], v[196:199], v[102:105]
	v_mfma_f32_16x16x32_bf16 v[78:81], v[180:183], v[204:207], v[78:81]
	v_mfma_f32_16x16x32_bf16 v[74:77], v[188:191], v[204:207], v[74:77]
	v_mfma_f32_16x16x32_bf16 v[30:33], v[180:183], v[212:215], v[30:33]
	v_mfma_f32_16x16x32_bf16 v[26:29], v[188:191], v[212:215], v[26:29]
	v_mfma_f32_16x16x32_bf16 v[10:13], v[180:183], v[220:223], v[10:13]
	v_mfma_f32_16x16x32_bf16 v[2:5], v[188:191], v[220:223], v[2:5]
	s_barrier
	s_add_u32 s56, s56, 0x100
	s_addc_u32 s57, s57, 0
	s_add_u32 s83, s83, 0x100
	s_addc_u32 s84, s84, 0
	s_cmp_ge_i32 s25, s78
	s_mov_b32 s24, s25
	s_cbranch_scc0 .LBB0_587
	s_and_b64 vcc, exec, s[14:15]
	s_cbranch_vccz .LBB0_592
	s_barrier
	s_mov_b64 s[56:57], -1
	s_cmp_lg_u32 s5, 1
	v_lshl_or_b32 v150, s71, 8, v139
	s_cbranch_scc1 .LBB0_593

.LBB0_908:
	s_add_u32 s23, s50, s24
	s_addc_u32 s35, s51, 0
	s_add_u32 s25, s23, 0x100
	s_addc_u32 s58, s35, 0
	s_and_b64 s[56:57], s[54:55], exec
	s_cselect_b32 s59, s19, s58
	s_cselect_b32 s58, s29, s25
	s_add_u32 s24, s48, s24
	s_addc_u32 s25, s49, 0
	s_add_u32 s56, s24, 0x100
	s_addc_u32 s57, s25, 0
	s_and_b64 s[24:25], s[54:55], exec
	s_cselect_b32 s61, s79, s57
	s_cselect_b32 s60, s80, s56
	s_add_u32 s64, s23, 0x40080
	s_addc_u32 s65, s35, 0
	s_add_i32 s88, s76, s68
	ds_read_b128 v[130:133], v179
	ds_read_b128 v[134:137], v179 offset:1024
	ds_read_b128 v[138:141], v179 offset:2048
	ds_read_b128 v[142:145], v179 offset:3072
	ds_read_b128 v[146:149], v180
	ds_read_b128 v[150:153], v180 offset:1024
	ds_read_b128 v[154:157], v180 offset:2048
	ds_read_b128 v[158:161], v180 offset:3072
	s_add_i32 m0, s47, 0xc000
	s_add_i32 s89, s47, 0xe000
	s_add_i32 s85, s88, 0x2000
	s_add_u32 s62, s60, 0x10000
	s_addc_u32 s63, s61, 0
	s_add_i32 s87, s77, s68
	s_add_i32 s86, s87, 0x2000
	s_add_i32 s84, 0, 0x18000
	s_add_i32 s83, 0, 0x1c000
	s_add_u32 s56, s58, 0x40000
	s_addc_u32 s57, s59, 0
	s_add_i32 s82, s84, s68
	s_add_i32 s25, s82, 0x2000
	s_add_u32 s54, s60, 0x10080
	s_addc_u32 s55, s61, 0
	s_add_i32 s81, s83, s68
	s_add_i32 s24, s81, 0x2000
	v_lshl_add_u64 v[176:177], s[64:65], 0, v[164:165]
	ds_read_b128 v[182:185], v181
	ds_read_b128 v[186:189], v181 offset:1024
	ds_read_b128 v[190:193], v181 offset:2048
	ds_read_b128 v[194:197], v181 offset:3072
	ds_read_b128 v[198:201], v181 offset:4096
	ds_read_b128 v[202:205], v181 offset:5120
	ds_read_b128 v[206:209], v181 offset:6144
	ds_read_b128 v[210:213], v181 offset:7168
	global_load_lds_dwordx4 v[176:177], off
	v_lshl_add_u64 v[176:177], s[64:65], 0, v[168:169]
	s_mov_b32 m0, s89
	s_nop 0
	global_load_lds_dwordx4 v[176:177], off
	s_waitcnt vmcnt(8)
	s_waitcnt lgkmcnt(0)
	s_barrier
	s_waitcnt lgkmcnt(0)
	v_mfma_f32_16x16x32_bf16 v[126:129], v[130:133], v[182:185], v[126:129]
	v_mfma_f32_16x16x32_bf16 v[122:125], v[138:141], v[182:185], v[122:125]
	v_mfma_f32_16x16x32_bf16 v[118:121], v[130:133], v[190:193], v[118:121]
	v_mfma_f32_16x16x32_bf16 v[114:117], v[138:141], v[190:193], v[114:117]
	v_mfma_f32_16x16x32_bf16 v[110:113], v[130:133], v[198:201], v[110:113]
	v_mfma_f32_16x16x32_bf16 v[98:101], v[138:141], v[198:201], v[98:101]
	v_mfma_f32_16x16x32_bf16 v[82:85], v[130:133], v[206:209], v[82:85]
	v_mfma_f32_16x16x32_bf16 v[74:77], v[138:141], v[206:209], v[74:77]
	v_mfma_f32_16x16x32_bf16 v[126:129], v[134:137], v[186:189], v[126:129]
	v_mfma_f32_16x16x32_bf16 v[122:125], v[142:145], v[186:189], v[122:125]
	v_mfma_f32_16x16x32_bf16 v[118:121], v[134:137], v[194:197], v[118:121]
	v_mfma_f32_16x16x32_bf16 v[114:117], v[142:145], v[194:197], v[114:117]
	v_mfma_f32_16x16x32_bf16 v[110:113], v[134:137], v[202:205], v[110:113]
	v_mfma_f32_16x16x32_bf16 v[98:101], v[142:145], v[202:205], v[98:101]
	v_mfma_f32_16x16x32_bf16 v[82:85], v[134:137], v[210:213], v[82:85]
	v_mfma_f32_16x16x32_bf16 v[74:77], v[142:145], v[210:213], v[74:77]
	v_mfma_f32_16x16x32_bf16 v[106:109], v[146:149], v[182:185], v[106:109]
	v_mfma_f32_16x16x32_bf16 v[102:105], v[154:157], v[182:185], v[102:105]
	v_mfma_f32_16x16x32_bf16 v[94:97], v[146:149], v[190:193], v[94:97]
	v_mfma_f32_16x16x32_bf16 v[90:93], v[154:157], v[190:193], v[90:93]
	v_mfma_f32_16x16x32_bf16 v[86:89], v[146:149], v[198:201], v[86:89]
	v_mfma_f32_16x16x32_bf16 v[78:81], v[154:157], v[198:201], v[78:81]
	v_mfma_f32_16x16x32_bf16 v[70:73], v[146:149], v[206:209], v[70:73]
	v_mfma_f32_16x16x32_bf16 v[66:69], v[154:157], v[206:209], v[66:69]
	v_mfma_f32_16x16x32_bf16 v[106:109], v[150:153], v[186:189], v[106:109]
	v_mfma_f32_16x16x32_bf16 v[102:105], v[158:161], v[186:189], v[102:105]
	v_mfma_f32_16x16x32_bf16 v[94:97], v[150:153], v[194:197], v[94:97]
	v_mfma_f32_16x16x32_bf16 v[90:93], v[158:161], v[194:197], v[90:93]
	v_mfma_f32_16x16x32_bf16 v[86:89], v[150:153], v[202:205], v[86:89]
	v_mfma_f32_16x16x32_bf16 v[78:81], v[158:161], v[202:205], v[78:81]
	v_mfma_f32_16x16x32_bf16 v[70:73], v[150:153], v[210:213], v[70:73]
	v_mfma_f32_16x16x32_bf16 v[66:69], v[158:161], v[210:213], v[66:69]
	s_barrier
	s_mov_b32 m0, s88
	v_lshl_add_u64 v[176:177], s[60:61], 0, v[166:167]
	ds_read_b128 v[182:185], v181 offset:16384
	ds_read_b128 v[186:189], v181 offset:17408
	ds_read_b128 v[190:193], v181 offset:18432
	ds_read_b128 v[194:197], v181 offset:19456
	ds_read_b128 v[198:201], v181 offset:20480
	ds_read_b128 v[202:205], v181 offset:21504
	ds_read_b128 v[206:209], v181 offset:22528
	ds_read_b128 v[210:213], v181 offset:23552
	global_load_lds_dwordx4 v[176:177], off
	v_lshl_add_u64 v[214:215], s[60:61], 0, v[170:171]
	s_mov_b32 m0, s85
	v_lshl_add_u64 v[216:217], s[62:63], 0, v[166:167]
	global_load_lds_dwordx4 v[214:215], off
	s_mov_b32 m0, s87
	v_lshl_add_u64 v[218:219], s[58:59], 0, v[168:169]
	global_load_lds_dwordx4 v[216:217], off
	v_lshl_add_u64 v[216:217], s[62:63], 0, v[170:171]
	s_mov_b32 m0, s86
	s_nop 0
	global_load_lds_dwordx4 v[216:217], off
	v_lshl_add_u64 v[216:217], s[58:59], 0, v[164:165]
	s_mov_b32 m0, s47
	s_nop 0
	global_load_lds_dwordx4 v[216:217], off
	s_mov_b32 m0, s69
	s_nop 0
	global_load_lds_dwordx4 v[218:219], off
	s_waitcnt vmcnt(8)
	s_waitcnt lgkmcnt(0)
	s_barrier
	s_waitcnt lgkmcnt(0)
	v_mfma_f32_16x16x32_bf16 v[62:65], v[130:133], v[182:185], v[62:65]
	v_mfma_f32_16x16x32_bf16 v[58:61], v[138:141], v[182:185], v[58:61]
	v_mfma_f32_16x16x32_bf16 v[54:57], v[130:133], v[190:193], v[54:57]
	v_mfma_f32_16x16x32_bf16 v[46:49], v[138:141], v[190:193], v[46:49]
	v_mfma_f32_16x16x32_bf16 v[38:41], v[130:133], v[198:201], v[38:41]
	v_mfma_f32_16x16x32_bf16 v[30:33], v[138:141], v[198:201], v[30:33]
	v_mfma_f32_16x16x32_bf16 v[22:25], v[130:133], v[206:209], v[22:25]
	v_mfma_f32_16x16x32_bf16 v[14:17], v[138:141], v[206:209], v[14:17]
	v_mfma_f32_16x16x32_bf16 v[62:65], v[134:137], v[186:189], v[62:65]
	v_mfma_f32_16x16x32_bf16 v[58:61], v[142:145], v[186:189], v[58:61]
	v_mfma_f32_16x16x32_bf16 v[54:57], v[134:137], v[194:197], v[54:57]
	v_mfma_f32_16x16x32_bf16 v[46:49], v[142:145], v[194:197], v[46:49]
	v_mfma_f32_16x16x32_bf16 v[38:41], v[134:137], v[202:205], v[38:41]
	v_mfma_f32_16x16x32_bf16 v[30:33], v[142:145], v[202:205], v[30:33]
	v_mfma_f32_16x16x32_bf16 v[22:25], v[134:137], v[210:213], v[22:25]
	v_mfma_f32_16x16x32_bf16 v[14:17], v[142:145], v[210:213], v[14:17]
	v_mfma_f32_16x16x32_bf16 v[50:53], v[146:149], v[182:185], v[50:53]
	v_mfma_f32_16x16x32_bf16 v[42:45], v[154:157], v[182:185], v[42:45]
	v_mfma_f32_16x16x32_bf16 v[34:37], v[146:149], v[190:193], v[34:37]
	v_mfma_f32_16x16x32_bf16 v[26:29], v[154:157], v[190:193], v[26:29]
	v_mfma_f32_16x16x32_bf16 v[18:21], v[146:149], v[198:201], v[18:21]
	v_mfma_f32_16x16x32_bf16 v[10:13], v[154:157], v[198:201], v[10:13]
	v_mfma_f32_16x16x32_bf16 v[6:9], v[146:149], v[206:209], v[6:9]
	v_mfma_f32_16x16x32_bf16 v[2:5], v[154:157], v[206:209], v[2:5]
	v_mfma_f32_16x16x32_bf16 v[50:53], v[150:153], v[186:189], v[50:53]
	v_mfma_f32_16x16x32_bf16 v[42:45], v[158:161], v[186:189], v[42:45]
	v_mfma_f32_16x16x32_bf16 v[34:37], v[150:153], v[194:197], v[34:37]
	v_mfma_f32_16x16x32_bf16 v[26:29], v[158:161], v[194:197], v[26:29]
	v_mfma_f32_16x16x32_bf16 v[18:21], v[150:153], v[202:205], v[18:21]
	v_mfma_f32_16x16x32_bf16 v[10:13], v[158:161], v[202:205], v[10:13]
	v_mfma_f32_16x16x32_bf16 v[6:9], v[150:153], v[210:213], v[6:9]
	v_mfma_f32_16x16x32_bf16 v[2:5], v[158:161], v[210:213], v[2:5]
	s_barrier
	v_add_u32_e32 v142, s84, v163
	v_add_u32_e32 v158, s83, v163
	ds_read_b128 v[130:133], v142
	ds_read_b128 v[134:137], v142 offset:1024
	ds_read_b128 v[138:141], v142 offset:2048
	ds_read_b128 v[142:145], v142 offset:3072
	ds_read_b128 v[146:149], v158
	ds_read_b128 v[150:153], v158 offset:1024
	ds_read_b128 v[154:157], v158 offset:2048
	ds_read_b128 v[158:161], v158 offset:3072
	s_mov_b32 m0, s70
	v_lshl_add_u64 v[220:221], s[56:57], 0, v[164:165]
	ds_read_b128 v[182:185], v181 offset:32768
	ds_read_b128 v[186:189], v181 offset:33792
	ds_read_b128 v[190:193], v181 offset:34816
	ds_read_b128 v[194:197], v181 offset:35840
	ds_read_b128 v[198:201], v181 offset:36864
	ds_read_b128 v[202:205], v181 offset:37888
	ds_read_b128 v[206:209], v181 offset:38912
	ds_read_b128 v[210:213], v181 offset:39936
	global_load_lds_dwordx4 v[220:221], off
	v_lshl_add_u64 v[220:221], s[56:57], 0, v[168:169]
	s_mov_b32 m0, s71
	s_nop 0
	global_load_lds_dwordx4 v[220:221], off
	s_waitcnt vmcnt(8)
	s_waitcnt lgkmcnt(0)
	s_barrier
	s_waitcnt lgkmcnt(0)
	v_mfma_f32_16x16x32_bf16 v[126:129], v[130:133], v[182:185], v[126:129]
	v_mfma_f32_16x16x32_bf16 v[122:125], v[138:141], v[182:185], v[122:125]
	v_mfma_f32_16x16x32_bf16 v[118:121], v[130:133], v[190:193], v[118:121]
	v_mfma_f32_16x16x32_bf16 v[114:117], v[138:141], v[190:193], v[114:117]
	v_mfma_f32_16x16x32_bf16 v[110:113], v[130:133], v[198:201], v[110:113]
	v_mfma_f32_16x16x32_bf16 v[98:101], v[138:141], v[198:201], v[98:101]
	v_mfma_f32_16x16x32_bf16 v[82:85], v[130:133], v[206:209], v[82:85]
	v_mfma_f32_16x16x32_bf16 v[74:77], v[138:141], v[206:209], v[74:77]
	v_mfma_f32_16x16x32_bf16 v[126:129], v[134:137], v[186:189], v[126:129]
	v_mfma_f32_16x16x32_bf16 v[122:125], v[142:145], v[186:189], v[122:125]
	v_mfma_f32_16x16x32_bf16 v[118:121], v[134:137], v[194:197], v[118:121]
	v_mfma_f32_16x16x32_bf16 v[114:117], v[142:145], v[194:197], v[114:117]
	v_mfma_f32_16x16x32_bf16 v[110:113], v[134:137], v[202:205], v[110:113]
	v_mfma_f32_16x16x32_bf16 v[98:101], v[142:145], v[202:205], v[98:101]
	v_mfma_f32_16x16x32_bf16 v[82:85], v[134:137], v[210:213], v[82:85]
	v_mfma_f32_16x16x32_bf16 v[74:77], v[142:145], v[210:213], v[74:77]
	v_mfma_f32_16x16x32_bf16 v[106:109], v[146:149], v[182:185], v[106:109]
	v_mfma_f32_16x16x32_bf16 v[102:105], v[154:157], v[182:185], v[102:105]
	v_mfma_f32_16x16x32_bf16 v[94:97], v[146:149], v[190:193], v[94:97]
	v_mfma_f32_16x16x32_bf16 v[90:93], v[154:157], v[190:193], v[90:93]
	v_mfma_f32_16x16x32_bf16 v[86:89], v[146:149], v[198:201], v[86:89]
	v_mfma_f32_16x16x32_bf16 v[78:81], v[154:157], v[198:201], v[78:81]
	v_mfma_f32_16x16x32_bf16 v[70:73], v[146:149], v[206:209], v[70:73]
	v_mfma_f32_16x16x32_bf16 v[66:69], v[154:157], v[206:209], v[66:69]
	v_mfma_f32_16x16x32_bf16 v[106:109], v[150:153], v[186:189], v[106:109]
	v_mfma_f32_16x16x32_bf16 v[102:105], v[158:161], v[186:189], v[102:105]
	v_mfma_f32_16x16x32_bf16 v[94:97], v[150:153], v[194:197], v[94:97]
	v_mfma_f32_16x16x32_bf16 v[90:93], v[158:161], v[194:197], v[90:93]
	v_mfma_f32_16x16x32_bf16 v[86:89], v[150:153], v[202:205], v[86:89]
	v_mfma_f32_16x16x32_bf16 v[78:81], v[158:161], v[202:205], v[78:81]
	v_mfma_f32_16x16x32_bf16 v[70:73], v[150:153], v[210:213], v[70:73]
	v_mfma_f32_16x16x32_bf16 v[66:69], v[158:161], v[210:213], v[66:69]
	s_barrier
	s_mov_b32 m0, s82
	v_lshl_add_u64 v[176:177], v[176:177], 0, s[14:15]
	ds_read_b128 v[182:185], v181 offset:49152
	ds_read_b128 v[186:189], v181 offset:50176
	ds_read_b128 v[190:193], v181 offset:51200
	ds_read_b128 v[194:197], v181 offset:52224
	ds_read_b128 v[198:201], v181 offset:53248
	ds_read_b128 v[202:205], v181 offset:54272
	ds_read_b128 v[206:209], v181 offset:55296
	ds_read_b128 v[210:213], v181 offset:56320
	global_load_lds_dwordx4 v[176:177], off
	v_lshl_add_u64 v[176:177], v[214:215], 0, s[14:15]
	s_mov_b32 m0, s25
	s_nop 0
	global_load_lds_dwordx4 v[176:177], off
	v_lshl_add_u64 v[176:177], s[54:55], 0, v[166:167]
	s_mov_b32 m0, s81
	s_nop 0
	global_load_lds_dwordx4 v[176:177], off
	v_lshl_add_u64 v[176:177], s[54:55], 0, v[170:171]
	s_mov_b32 m0, s24
	s_nop 0
	global_load_lds_dwordx4 v[176:177], off
	v_lshl_add_u64 v[176:177], v[216:217], 0, s[14:15]
	s_mov_b32 m0, s73
	s_nop 0
	global_load_lds_dwordx4 v[176:177], off
	v_lshl_add_u64 v[176:177], v[218:219], 0, s[14:15]
	s_mov_b32 m0, s74
	s_nop 0
	global_load_lds_dwordx4 v[176:177], off
	s_waitcnt vmcnt(8)
	s_waitcnt lgkmcnt(0)
	s_barrier
	s_waitcnt lgkmcnt(0)
	v_mfma_f32_16x16x32_bf16 v[62:65], v[130:133], v[182:185], v[62:65]
	v_mfma_f32_16x16x32_bf16 v[58:61], v[138:141], v[182:185], v[58:61]
	v_mfma_f32_16x16x32_bf16 v[54:57], v[130:133], v[190:193], v[54:57]
	v_mfma_f32_16x16x32_bf16 v[46:49], v[138:141], v[190:193], v[46:49]
	v_mfma_f32_16x16x32_bf16 v[38:41], v[130:133], v[198:201], v[38:41]
	v_mfma_f32_16x16x32_bf16 v[30:33], v[138:141], v[198:201], v[30:33]
	v_mfma_f32_16x16x32_bf16 v[22:25], v[130:133], v[206:209], v[22:25]
	v_mfma_f32_16x16x32_bf16 v[14:17], v[138:141], v[206:209], v[14:17]
	v_mfma_f32_16x16x32_bf16 v[62:65], v[134:137], v[186:189], v[62:65]
	v_mfma_f32_16x16x32_bf16 v[58:61], v[142:145], v[186:189], v[58:61]
	v_mfma_f32_16x16x32_bf16 v[54:57], v[134:137], v[194:197], v[54:57]
	v_mfma_f32_16x16x32_bf16 v[46:49], v[142:145], v[194:197], v[46:49]
	v_mfma_f32_16x16x32_bf16 v[38:41], v[134:137], v[202:205], v[38:41]
	v_mfma_f32_16x16x32_bf16 v[30:33], v[142:145], v[202:205], v[30:33]
	v_mfma_f32_16x16x32_bf16 v[22:25], v[134:137], v[210:213], v[22:25]
	v_mfma_f32_16x16x32_bf16 v[14:17], v[142:145], v[210:213], v[14:17]
	v_mfma_f32_16x16x32_bf16 v[50:53], v[146:149], v[182:185], v[50:53]
	v_mfma_f32_16x16x32_bf16 v[42:45], v[154:157], v[182:185], v[42:45]
	v_mfma_f32_16x16x32_bf16 v[34:37], v[146:149], v[190:193], v[34:37]
	v_mfma_f32_16x16x32_bf16 v[26:29], v[154:157], v[190:193], v[26:29]
	v_mfma_f32_16x16x32_bf16 v[18:21], v[146:149], v[198:201], v[18:21]
	v_mfma_f32_16x16x32_bf16 v[10:13], v[154:157], v[198:201], v[10:13]
	v_mfma_f32_16x16x32_bf16 v[6:9], v[146:149], v[206:209], v[6:9]
	v_mfma_f32_16x16x32_bf16 v[2:5], v[154:157], v[206:209], v[2:5]
	v_mfma_f32_16x16x32_bf16 v[50:53], v[150:153], v[186:189], v[50:53]
	v_mfma_f32_16x16x32_bf16 v[42:45], v[158:161], v[186:189], v[42:45]
	v_mfma_f32_16x16x32_bf16 v[34:37], v[150:153], v[194:197], v[34:37]
	v_mfma_f32_16x16x32_bf16 v[26:29], v[158:161], v[194:197], v[26:29]
	v_mfma_f32_16x16x32_bf16 v[18:21], v[150:153], v[202:205], v[18:21]
	v_mfma_f32_16x16x32_bf16 v[10:13], v[158:161], v[202:205], v[10:13]
	v_mfma_f32_16x16x32_bf16 v[6:9], v[150:153], v[210:213], v[6:9]
	v_mfma_f32_16x16x32_bf16 v[2:5], v[158:161], v[210:213], v[2:5]
	s_barrier
	s_movk_i32 s24, 0x100
	s_andn2_b64 vcc, exec, s[52:53]
	s_mov_b64 s[54:55], -1
	s_mov_b64 s[52:53], 0
	s_cbranch_vccz .LBB0_908
	s_and_b64 vcc, exec, s[16:17]
	s_cbranch_vccz .LBB0_911
	s_barrier

.LBB0_995:
	ds_read_b128 v[148:151], v160
	ds_read_b128 v[152:155], v160 offset:1024
	ds_read_b128 v[164:167], v160 offset:2048
	ds_read_b128 v[168:171], v160 offset:3072
	ds_read_b128 v[172:175], v161
	ds_read_b128 v[176:179], v161 offset:1024
	ds_read_b128 v[180:183], v161 offset:2048
	ds_read_b128 v[184:187], v161 offset:3072
	s_add_i32 s25, s24, 2
	s_add_u32 s23, s48, 0xfff80080
	s_addc_u32 s35, s49, -1
	s_cmp_eq_u32 s75, s24
	s_cselect_b32 s53, s15, s35
	s_cselect_b32 s52, s31, s23
	s_cselect_b32 s51, s73, s77
	s_cselect_b32 s50, s74, s76
	s_cselect_b64 s[100:101], s[38:39], -1
	v_lshl_add_u64 v[156:157], s[48:49], 0, v[140:141]
	s_add_i32 m0, s55, 0xc000
	ds_read_b128 v[188:191], v163
	ds_read_b128 v[192:195], v163 offset:1024
	ds_read_b128 v[196:199], v163 offset:2048
	ds_read_b128 v[200:203], v163 offset:3072
	ds_read_b128 v[204:207], v163 offset:4096
	ds_read_b128 v[208:211], v163 offset:5120
	ds_read_b128 v[212:215], v163 offset:6144
	ds_read_b128 v[216:219], v163 offset:7168
	global_load_lds_dwordx4 v[156:157], off
	v_lshl_add_u64 v[156:157], s[48:49], 0, v[142:143]
	s_add_i32 m0, s55, 0xe000
	s_nop 0
	global_load_lds_dwordx4 v[156:157], off
	s_waitcnt vmcnt(8)
	s_waitcnt lgkmcnt(0)
	s_barrier
	s_waitcnt lgkmcnt(0)
	v_mfma_f32_16x16x32_bf16 v[78:81], v[148:151], v[188:191], v[78:81]
	v_mfma_f32_16x16x32_bf16 v[74:77], v[164:167], v[188:191], v[74:77]
	v_mfma_f32_16x16x32_bf16 v[70:73], v[148:151], v[196:199], v[70:73]
	v_mfma_f32_16x16x32_bf16 v[62:65], v[164:167], v[196:199], v[62:65]
	v_mfma_f32_16x16x32_bf16 v[54:57], v[148:151], v[204:207], v[54:57]
	v_mfma_f32_16x16x32_bf16 v[46:49], v[164:167], v[204:207], v[46:49]
	v_mfma_f32_16x16x32_bf16 v[38:41], v[148:151], v[212:215], v[38:41]
	v_mfma_f32_16x16x32_bf16 v[30:33], v[164:167], v[212:215], v[30:33]
	v_mfma_f32_16x16x32_bf16 v[78:81], v[152:155], v[192:195], v[78:81]
	v_mfma_f32_16x16x32_bf16 v[74:77], v[168:171], v[192:195], v[74:77]
	v_mfma_f32_16x16x32_bf16 v[70:73], v[152:155], v[200:203], v[70:73]
	v_mfma_f32_16x16x32_bf16 v[62:65], v[168:171], v[200:203], v[62:65]
	v_mfma_f32_16x16x32_bf16 v[54:57], v[152:155], v[208:211], v[54:57]
	v_mfma_f32_16x16x32_bf16 v[46:49], v[168:171], v[208:211], v[46:49]
	v_mfma_f32_16x16x32_bf16 v[38:41], v[152:155], v[216:219], v[38:41]
	v_mfma_f32_16x16x32_bf16 v[30:33], v[168:171], v[216:219], v[30:33]
	v_mfma_f32_16x16x32_bf16 v[50:53], v[172:175], v[188:191], v[50:53]
	v_mfma_f32_16x16x32_bf16 v[42:45], v[180:183], v[188:191], v[42:45]
	v_mfma_f32_16x16x32_bf16 v[34:37], v[172:175], v[196:199], v[34:37]
	v_mfma_f32_16x16x32_bf16 v[26:29], v[180:183], v[196:199], v[26:29]
	v_mfma_f32_16x16x32_bf16 v[22:25], v[172:175], v[204:207], v[22:25]
	v_mfma_f32_16x16x32_bf16 v[18:21], v[180:183], v[204:207], v[18:21]
	v_mfma_f32_16x16x32_bf16 v[10:13], v[172:175], v[212:215], v[10:13]
	v_mfma_f32_16x16x32_bf16 v[6:9], v[180:183], v[212:215], v[6:9]
	v_mfma_f32_16x16x32_bf16 v[50:53], v[176:179], v[192:195], v[50:53]
	v_mfma_f32_16x16x32_bf16 v[42:45], v[184:187], v[192:195], v[42:45]
	v_mfma_f32_16x16x32_bf16 v[34:37], v[176:179], v[200:203], v[34:37]
	v_mfma_f32_16x16x32_bf16 v[26:29], v[184:187], v[200:203], v[26:29]
	v_mfma_f32_16x16x32_bf16 v[22:25], v[176:179], v[208:211], v[22:25]
	v_mfma_f32_16x16x32_bf16 v[18:21], v[184:187], v[208:211], v[18:21]
	v_mfma_f32_16x16x32_bf16 v[10:13], v[176:179], v[216:219], v[10:13]
	v_mfma_f32_16x16x32_bf16 v[6:9], v[184:187], v[216:219], v[6:9]
	s_barrier
	s_add_i32 s23, s68, s54
	v_lshl_add_u64 v[156:157], s[50:51], 0, v[132:133]
	s_mov_b32 m0, s23
	ds_read_b128 v[188:191], v163 offset:16384
	ds_read_b128 v[192:195], v163 offset:17408
	ds_read_b128 v[196:199], v163 offset:18432
	ds_read_b128 v[200:203], v163 offset:19456
	ds_read_b128 v[204:207], v163 offset:20480
	ds_read_b128 v[208:211], v163 offset:21504
	ds_read_b128 v[212:215], v163 offset:22528
	ds_read_b128 v[216:219], v163 offset:23552
	global_load_lds_dwordx4 v[156:157], off
	s_add_i32 m0, s23, 0x2000
	s_add_u32 s78, s50, 0x80000
	v_lshl_add_u64 v[220:221], s[50:51], 0, v[136:137]
	s_addc_u32 s79, s51, 0
	s_add_i32 s23, s69, s54
	global_load_lds_dwordx4 v[220:221], off
	v_lshl_add_u64 v[222:223], s[78:79], 0, v[132:133]
	s_mov_b32 m0, s23
	v_lshl_add_u64 v[224:225], s[52:53], 0, v[134:135]
	global_load_lds_dwordx4 v[222:223], off
	v_lshl_add_u64 v[222:223], s[78:79], 0, v[136:137]
	s_add_i32 m0, s23, 0x2000
	s_nop 0
	global_load_lds_dwordx4 v[222:223], off
	v_lshl_add_u64 v[222:223], s[52:53], 0, v[130:131]
	s_mov_b32 m0, s55
	s_nop 0
	global_load_lds_dwordx4 v[222:223], off
	s_mov_b32 m0, s56
	s_nop 0
	global_load_lds_dwordx4 v[224:225], off
	s_waitcnt vmcnt(8)
	s_waitcnt lgkmcnt(0)
	s_barrier
	s_waitcnt lgkmcnt(0)
	v_mfma_f32_16x16x32_bf16 v[126:129], v[148:151], v[188:191], v[126:129]
	v_mfma_f32_16x16x32_bf16 v[122:125], v[164:167], v[188:191], v[122:125]
	v_mfma_f32_16x16x32_bf16 v[110:113], v[148:151], v[196:199], v[110:113]
	v_mfma_f32_16x16x32_bf16 v[106:109], v[164:167], v[196:199], v[106:109]
	v_mfma_f32_16x16x32_bf16 v[94:97], v[148:151], v[204:207], v[94:97]
	v_mfma_f32_16x16x32_bf16 v[90:93], v[164:167], v[204:207], v[90:93]
	v_mfma_f32_16x16x32_bf16 v[66:69], v[148:151], v[212:215], v[66:69]
	v_mfma_f32_16x16x32_bf16 v[58:61], v[164:167], v[212:215], v[58:61]
	v_mfma_f32_16x16x32_bf16 v[126:129], v[152:155], v[192:195], v[126:129]
	v_mfma_f32_16x16x32_bf16 v[122:125], v[168:171], v[192:195], v[122:125]
	v_mfma_f32_16x16x32_bf16 v[110:113], v[152:155], v[200:203], v[110:113]
	v_mfma_f32_16x16x32_bf16 v[106:109], v[168:171], v[200:203], v[106:109]
	v_mfma_f32_16x16x32_bf16 v[94:97], v[152:155], v[208:211], v[94:97]
	v_mfma_f32_16x16x32_bf16 v[90:93], v[168:171], v[208:211], v[90:93]
	v_mfma_f32_16x16x32_bf16 v[66:69], v[152:155], v[216:219], v[66:69]
	v_mfma_f32_16x16x32_bf16 v[58:61], v[168:171], v[216:219], v[58:61]
	v_mfma_f32_16x16x32_bf16 v[118:121], v[172:175], v[188:191], v[118:121]
	v_mfma_f32_16x16x32_bf16 v[114:117], v[180:183], v[188:191], v[114:117]
	v_mfma_f32_16x16x32_bf16 v[102:105], v[172:175], v[196:199], v[102:105]
	v_mfma_f32_16x16x32_bf16 v[98:101], v[180:183], v[196:199], v[98:101]
	v_mfma_f32_16x16x32_bf16 v[86:89], v[172:175], v[204:207], v[86:89]
	v_mfma_f32_16x16x32_bf16 v[82:85], v[180:183], v[204:207], v[82:85]
	v_mfma_f32_16x16x32_bf16 v[14:17], v[172:175], v[212:215], v[14:17]
	v_mfma_f32_16x16x32_bf16 v[2:5], v[180:183], v[212:215], v[2:5]
	v_mfma_f32_16x16x32_bf16 v[118:121], v[176:179], v[192:195], v[118:121]
	v_mfma_f32_16x16x32_bf16 v[114:117], v[184:187], v[192:195], v[114:117]
	v_mfma_f32_16x16x32_bf16 v[102:105], v[176:179], v[200:203], v[102:105]
	v_mfma_f32_16x16x32_bf16 v[98:101], v[184:187], v[200:203], v[98:101]
	v_mfma_f32_16x16x32_bf16 v[86:89], v[176:179], v[208:211], v[86:89]
	v_mfma_f32_16x16x32_bf16 v[82:85], v[184:187], v[208:211], v[82:85]
	v_mfma_f32_16x16x32_bf16 v[14:17], v[176:179], v[216:219], v[14:17]
	v_mfma_f32_16x16x32_bf16 v[2:5], v[184:187], v[216:219], v[2:5]
	s_barrier
	s_add_i32 s23, 0, 0x18000
	s_add_i32 s24, 0, 0x1c000
	v_add_u32_e32 v168, s23, v158
	v_add_u32_e32 v184, s24, v158
	ds_read_b128 v[148:151], v168
	ds_read_b128 v[152:155], v168 offset:1024
	ds_read_b128 v[164:167], v168 offset:2048
	ds_read_b128 v[168:171], v168 offset:3072
	ds_read_b128 v[172:175], v184
	ds_read_b128 v[176:179], v184 offset:1024
	ds_read_b128 v[180:183], v184 offset:2048
	ds_read_b128 v[184:187], v184 offset:3072
	s_add_u32 s52, s52, 0x80000
	s_addc_u32 s53, s53, 0
	s_mov_b32 m0, s57
	v_lshl_add_u64 v[226:227], s[52:53], 0, v[130:131]
	ds_read_b128 v[188:191], v163 offset:32768
	ds_read_b128 v[192:195], v163 offset:33792
	ds_read_b128 v[196:199], v163 offset:34816
	ds_read_b128 v[200:203], v163 offset:35840
	ds_read_b128 v[204:207], v163 offset:36864
	ds_read_b128 v[208:211], v163 offset:37888
	ds_read_b128 v[212:215], v163 offset:38912
	ds_read_b128 v[216:219], v163 offset:39936
	s_mov_b64 exec, s[100:101]
	global_load_lds_dwordx4 v[226:227], off
	s_mov_b64 exec, -1
	v_lshl_add_u64 v[226:227], s[52:53], 0, v[134:135]
	s_mov_b32 m0, s58
	s_nop 0
	s_mov_b64 exec, s[100:101]
	global_load_lds_dwordx4 v[226:227], off
	s_mov_b64 exec, -1
	s_waitcnt vmcnt(8)
	s_waitcnt lgkmcnt(0)
	s_barrier
	s_waitcnt lgkmcnt(0)
	v_mfma_f32_16x16x32_bf16 v[78:81], v[148:151], v[188:191], v[78:81]
	v_mfma_f32_16x16x32_bf16 v[74:77], v[164:167], v[188:191], v[74:77]
	v_mfma_f32_16x16x32_bf16 v[70:73], v[148:151], v[196:199], v[70:73]
	v_mfma_f32_16x16x32_bf16 v[62:65], v[164:167], v[196:199], v[62:65]
	v_mfma_f32_16x16x32_bf16 v[54:57], v[148:151], v[204:207], v[54:57]
	v_mfma_f32_16x16x32_bf16 v[46:49], v[164:167], v[204:207], v[46:49]
	v_mfma_f32_16x16x32_bf16 v[38:41], v[148:151], v[212:215], v[38:41]
	v_mfma_f32_16x16x32_bf16 v[30:33], v[164:167], v[212:215], v[30:33]
	v_mfma_f32_16x16x32_bf16 v[78:81], v[152:155], v[192:195], v[78:81]
	v_mfma_f32_16x16x32_bf16 v[74:77], v[168:171], v[192:195], v[74:77]
	v_mfma_f32_16x16x32_bf16 v[70:73], v[152:155], v[200:203], v[70:73]
	v_mfma_f32_16x16x32_bf16 v[62:65], v[168:171], v[200:203], v[62:65]
	v_mfma_f32_16x16x32_bf16 v[54:57], v[152:155], v[208:211], v[54:57]
	v_mfma_f32_16x16x32_bf16 v[46:49], v[168:171], v[208:211], v[46:49]
	v_mfma_f32_16x16x32_bf16 v[38:41], v[152:155], v[216:219], v[38:41]
	v_mfma_f32_16x16x32_bf16 v[30:33], v[168:171], v[216:219], v[30:33]
	v_mfma_f32_16x16x32_bf16 v[50:53], v[172:175], v[188:191], v[50:53]
	v_mfma_f32_16x16x32_bf16 v[42:45], v[180:183], v[188:191], v[42:45]
	v_mfma_f32_16x16x32_bf16 v[34:37], v[172:175], v[196:199], v[34:37]
	v_mfma_f32_16x16x32_bf16 v[26:29], v[180:183], v[196:199], v[26:29]
	v_mfma_f32_16x16x32_bf16 v[22:25], v[172:175], v[204:207], v[22:25]
	v_mfma_f32_16x16x32_bf16 v[18:21], v[180:183], v[204:207], v[18:21]
	v_mfma_f32_16x16x32_bf16 v[10:13], v[172:175], v[212:215], v[10:13]
	v_mfma_f32_16x16x32_bf16 v[6:9], v[180:183], v[212:215], v[6:9]
	v_mfma_f32_16x16x32_bf16 v[50:53], v[176:179], v[192:195], v[50:53]
	v_mfma_f32_16x16x32_bf16 v[42:45], v[184:187], v[192:195], v[42:45]
	v_mfma_f32_16x16x32_bf16 v[34:37], v[176:179], v[200:203], v[34:37]
	v_mfma_f32_16x16x32_bf16 v[26:29], v[184:187], v[200:203], v[26:29]
	v_mfma_f32_16x16x32_bf16 v[22:25], v[176:179], v[208:211], v[22:25]
	v_mfma_f32_16x16x32_bf16 v[18:21], v[184:187], v[208:211], v[18:21]
	v_mfma_f32_16x16x32_bf16 v[10:13], v[176:179], v[216:219], v[10:13]
	v_mfma_f32_16x16x32_bf16 v[6:9], v[184:187], v[216:219], v[6:9]
	s_barrier
	s_add_i32 s23, s23, s54
	v_lshl_add_u64 v[156:157], v[156:157], 0, s[8:9]
	s_mov_b32 m0, s23
	ds_read_b128 v[188:191], v163 offset:49152
	ds_read_b128 v[192:195], v163 offset:50176
	ds_read_b128 v[196:199], v163 offset:51200
	ds_read_b128 v[200:203], v163 offset:52224
	ds_read_b128 v[204:207], v163 offset:53248
	ds_read_b128 v[208:211], v163 offset:54272
	ds_read_b128 v[212:215], v163 offset:55296
	ds_read_b128 v[216:219], v163 offset:56320
	s_mov_b64 exec, s[100:101]
	global_load_lds_dwordx4 v[156:157], off
	s_mov_b64 exec, -1
	s_add_i32 m0, s23, 0x2000
	s_add_u32 s50, s50, 0x80080
	v_lshl_add_u64 v[156:157], v[220:221], 0, s[8:9]
	s_addc_u32 s51, s51, 0
	s_add_i32 s23, s24, s54
	s_mov_b64 exec, s[100:101]
	global_load_lds_dwordx4 v[156:157], off
	s_mov_b64 exec, -1
	v_lshl_add_u64 v[156:157], s[50:51], 0, v[132:133]
	s_mov_b32 m0, s23
	s_nop 0
	s_mov_b64 exec, s[100:101]
	global_load_lds_dwordx4 v[156:157], off
	s_mov_b64 exec, -1
	v_lshl_add_u64 v[156:157], s[50:51], 0, v[136:137]
	s_add_i32 m0, s23, 0x2000
	s_nop 0
	s_mov_b64 exec, s[100:101]
	global_load_lds_dwordx4 v[156:157], off
	s_mov_b64 exec, -1
	v_lshl_add_u64 v[156:157], v[222:223], 0, s[8:9]
	s_mov_b32 m0, s63
	s_nop 0
	s_mov_b64 exec, s[100:101]
	global_load_lds_dwordx4 v[156:157], off
	s_mov_b64 exec, -1
	v_lshl_add_u64 v[156:157], v[224:225], 0, s[8:9]
	s_mov_b32 m0, s64
	s_nop 0
	s_mov_b64 exec, s[100:101]
	global_load_lds_dwordx4 v[156:157], off
	s_mov_b64 exec, -1
	s_waitcnt vmcnt(8)
	s_waitcnt lgkmcnt(0)
	s_barrier
	s_waitcnt lgkmcnt(0)
	v_mfma_f32_16x16x32_bf16 v[126:129], v[148:151], v[188:191], v[126:129]
	v_mfma_f32_16x16x32_bf16 v[122:125], v[164:167], v[188:191], v[122:125]
	v_mfma_f32_16x16x32_bf16 v[110:113], v[148:151], v[196:199], v[110:113]
	v_mfma_f32_16x16x32_bf16 v[106:109], v[164:167], v[196:199], v[106:109]
	v_mfma_f32_16x16x32_bf16 v[94:97], v[148:151], v[204:207], v[94:97]
	v_mfma_f32_16x16x32_bf16 v[90:93], v[164:167], v[204:207], v[90:93]
	v_mfma_f32_16x16x32_bf16 v[66:69], v[148:151], v[212:215], v[66:69]
	v_mfma_f32_16x16x32_bf16 v[58:61], v[164:167], v[212:215], v[58:61]
	v_mfma_f32_16x16x32_bf16 v[126:129], v[152:155], v[192:195], v[126:129]
	v_mfma_f32_16x16x32_bf16 v[122:125], v[168:171], v[192:195], v[122:125]
	v_mfma_f32_16x16x32_bf16 v[110:113], v[152:155], v[200:203], v[110:113]
	v_mfma_f32_16x16x32_bf16 v[106:109], v[168:171], v[200:203], v[106:109]
	v_mfma_f32_16x16x32_bf16 v[94:97], v[152:155], v[208:211], v[94:97]
	v_mfma_f32_16x16x32_bf16 v[90:93], v[168:171], v[208:211], v[90:93]
	v_mfma_f32_16x16x32_bf16 v[66:69], v[152:155], v[216:219], v[66:69]
	v_mfma_f32_16x16x32_bf16 v[58:61], v[168:171], v[216:219], v[58:61]
	v_mfma_f32_16x16x32_bf16 v[118:121], v[172:175], v[188:191], v[118:121]
	v_mfma_f32_16x16x32_bf16 v[114:117], v[180:183], v[188:191], v[114:117]
	v_mfma_f32_16x16x32_bf16 v[102:105], v[172:175], v[196:199], v[102:105]
	v_mfma_f32_16x16x32_bf16 v[98:101], v[180:183], v[196:199], v[98:101]
	v_mfma_f32_16x16x32_bf16 v[86:89], v[172:175], v[204:207], v[86:89]
	v_mfma_f32_16x16x32_bf16 v[82:85], v[180:183], v[204:207], v[82:85]
	v_mfma_f32_16x16x32_bf16 v[14:17], v[172:175], v[212:215], v[14:17]
	v_mfma_f32_16x16x32_bf16 v[2:5], v[180:183], v[212:215], v[2:5]
	v_mfma_f32_16x16x32_bf16 v[118:121], v[176:179], v[192:195], v[118:121]
	v_mfma_f32_16x16x32_bf16 v[114:117], v[184:187], v[192:195], v[114:117]
	v_mfma_f32_16x16x32_bf16 v[102:105], v[176:179], v[200:203], v[102:105]
	v_mfma_f32_16x16x32_bf16 v[98:101], v[184:187], v[200:203], v[98:101]
	v_mfma_f32_16x16x32_bf16 v[86:89], v[176:179], v[208:211], v[86:89]
	v_mfma_f32_16x16x32_bf16 v[82:85], v[184:187], v[208:211], v[82:85]
	v_mfma_f32_16x16x32_bf16 v[14:17], v[176:179], v[216:219], v[14:17]
	v_mfma_f32_16x16x32_bf16 v[2:5], v[184:187], v[216:219], v[2:5]
	s_barrier
	s_add_u32 s48, s48, 0x100
	s_addc_u32 s49, s49, 0
	s_add_u32 s76, s76, 0x100
	s_addc_u32 s77, s77, 0
	s_cmp_ge_i32 s25, s72
	s_mov_b32 s24, s25
	s_cbranch_scc0 .LBB0_995
	s_and_b64 vcc, exec, s[10:11]
	s_cbranch_vccz .LBB0_998
	s_barrier

.LBB0_1149:
	ds_read_b128 v[154:157], v150
	ds_read_b128 v[158:161], v150 offset:1024
	ds_read_b128 v[164:167], v150 offset:2048
	ds_read_b128 v[168:171], v150 offset:3072
	ds_read_b128 v[172:175], v151
	ds_read_b128 v[176:179], v151 offset:1024
	ds_read_b128 v[180:183], v151 offset:2048
	ds_read_b128 v[184:187], v151 offset:3072
	s_add_u32 s23, s42, 0xfff80080
	s_addc_u32 s24, s43, -1
	s_cmp_eq_u32 s64, 28
	s_cselect_b32 s47, s13, s24
	s_cselect_b32 s46, s15, s23
	s_cselect_b32 s45, s60, s63
	s_cselect_b32 s44, s61, s62
	v_lshl_add_u64 v[146:147], s[42:43], 0, v[138:139]
	s_add_i32 m0, s39, 0xc000
	ds_read_b128 v[188:191], v152
	ds_read_b128 v[192:195], v152 offset:1024
	ds_read_b128 v[196:199], v152 offset:2048
	ds_read_b128 v[200:203], v152 offset:3072
	ds_read_b128 v[204:207], v152 offset:4096
	ds_read_b128 v[208:211], v152 offset:5120
	ds_read_b128 v[212:215], v152 offset:6144
	ds_read_b128 v[216:219], v152 offset:7168
	global_load_lds_dwordx4 v[146:147], off
	v_lshl_add_u64 v[146:147], s[42:43], 0, v[140:141]
	s_add_i32 m0, s39, 0xe000
	s_nop 0
	global_load_lds_dwordx4 v[146:147], off
	s_waitcnt vmcnt(8)
	s_waitcnt lgkmcnt(0)
	s_barrier
	s_waitcnt lgkmcnt(0)
	v_mfma_f32_16x16x32_bf16 v[126:129], v[154:157], v[188:191], v[126:129]
	v_mfma_f32_16x16x32_bf16 v[122:125], v[164:167], v[188:191], v[122:125]
	v_mfma_f32_16x16x32_bf16 v[110:113], v[154:157], v[196:199], v[110:113]
	v_mfma_f32_16x16x32_bf16 v[106:109], v[164:167], v[196:199], v[106:109]
	v_mfma_f32_16x16x32_bf16 v[94:97], v[154:157], v[204:207], v[94:97]
	v_mfma_f32_16x16x32_bf16 v[90:93], v[164:167], v[204:207], v[90:93]
	v_mfma_f32_16x16x32_bf16 v[78:81], v[154:157], v[212:215], v[78:81]
	v_mfma_f32_16x16x32_bf16 v[74:77], v[164:167], v[212:215], v[74:77]
	v_mfma_f32_16x16x32_bf16 v[126:129], v[158:161], v[192:195], v[126:129]
	v_mfma_f32_16x16x32_bf16 v[122:125], v[168:171], v[192:195], v[122:125]
	v_mfma_f32_16x16x32_bf16 v[110:113], v[158:161], v[200:203], v[110:113]
	v_mfma_f32_16x16x32_bf16 v[106:109], v[168:171], v[200:203], v[106:109]
	v_mfma_f32_16x16x32_bf16 v[94:97], v[158:161], v[208:211], v[94:97]
	v_mfma_f32_16x16x32_bf16 v[90:93], v[168:171], v[208:211], v[90:93]
	v_mfma_f32_16x16x32_bf16 v[78:81], v[158:161], v[216:219], v[78:81]
	v_mfma_f32_16x16x32_bf16 v[74:77], v[168:171], v[216:219], v[74:77]
	v_mfma_f32_16x16x32_bf16 v[118:121], v[172:175], v[188:191], v[118:121]
	v_mfma_f32_16x16x32_bf16 v[114:117], v[180:183], v[188:191], v[114:117]
	v_mfma_f32_16x16x32_bf16 v[102:105], v[172:175], v[196:199], v[102:105]
	v_mfma_f32_16x16x32_bf16 v[98:101], v[180:183], v[196:199], v[98:101]
	v_mfma_f32_16x16x32_bf16 v[86:89], v[172:175], v[204:207], v[86:89]
	v_mfma_f32_16x16x32_bf16 v[82:85], v[180:183], v[204:207], v[82:85]
	v_mfma_f32_16x16x32_bf16 v[70:73], v[172:175], v[212:215], v[70:73]
	v_mfma_f32_16x16x32_bf16 v[66:69], v[180:183], v[212:215], v[66:69]
	v_mfma_f32_16x16x32_bf16 v[118:121], v[176:179], v[192:195], v[118:121]
	v_mfma_f32_16x16x32_bf16 v[114:117], v[184:187], v[192:195], v[114:117]
	v_mfma_f32_16x16x32_bf16 v[102:105], v[176:179], v[200:203], v[102:105]
	v_mfma_f32_16x16x32_bf16 v[98:101], v[184:187], v[200:203], v[98:101]
	v_mfma_f32_16x16x32_bf16 v[86:89], v[176:179], v[208:211], v[86:89]
	v_mfma_f32_16x16x32_bf16 v[82:85], v[184:187], v[208:211], v[82:85]
	v_mfma_f32_16x16x32_bf16 v[70:73], v[176:179], v[216:219], v[70:73]
	v_mfma_f32_16x16x32_bf16 v[66:69], v[184:187], v[216:219], v[66:69]
	s_barrier
	s_add_i32 s23, s56, s48
	v_lshl_add_u64 v[146:147], s[44:45], 0, v[132:133]
	s_mov_b32 m0, s23
	ds_read_b128 v[188:191], v152 offset:16384
	ds_read_b128 v[192:195], v152 offset:17408
	ds_read_b128 v[196:199], v152 offset:18432
	ds_read_b128 v[200:203], v152 offset:19456
	ds_read_b128 v[204:207], v152 offset:20480
	ds_read_b128 v[208:211], v152 offset:21504
	ds_read_b128 v[212:215], v152 offset:22528
	ds_read_b128 v[216:219], v152 offset:23552
	global_load_lds_dwordx4 v[146:147], off
	s_add_i32 m0, s23, 0x2000
	s_add_u32 s24, s44, 0x80000
	v_lshl_add_u64 v[220:221], s[44:45], 0, v[136:137]
	s_addc_u32 s25, s45, 0
	s_add_i32 s23, s57, s48
	global_load_lds_dwordx4 v[220:221], off
	v_lshl_add_u64 v[222:223], s[24:25], 0, v[132:133]
	s_mov_b32 m0, s23
	v_lshl_add_u64 v[224:225], s[46:47], 0, v[134:135]
	global_load_lds_dwordx4 v[222:223], off
	v_lshl_add_u64 v[222:223], s[24:25], 0, v[136:137]
	s_add_i32 m0, s23, 0x2000
	s_nop 0
	global_load_lds_dwordx4 v[222:223], off
	v_lshl_add_u64 v[222:223], s[46:47], 0, v[130:131]
	s_mov_b32 m0, s39
	s_nop 0
	global_load_lds_dwordx4 v[222:223], off
	s_mov_b32 m0, s49
	s_nop 0
	global_load_lds_dwordx4 v[224:225], off
	s_waitcnt vmcnt(8)
	s_waitcnt lgkmcnt(0)
	s_barrier
	s_waitcnt lgkmcnt(0)
	v_mfma_f32_16x16x32_bf16 v[62:65], v[154:157], v[188:191], v[62:65]
	v_mfma_f32_16x16x32_bf16 v[58:61], v[164:167], v[188:191], v[58:61]
	v_mfma_f32_16x16x32_bf16 v[46:49], v[154:157], v[196:199], v[46:49]
	v_mfma_f32_16x16x32_bf16 v[42:45], v[164:167], v[196:199], v[42:45]
	v_mfma_f32_16x16x32_bf16 v[30:33], v[154:157], v[204:207], v[30:33]
	v_mfma_f32_16x16x32_bf16 v[26:29], v[164:167], v[204:207], v[26:29]
	v_mfma_f32_16x16x32_bf16 v[14:17], v[154:157], v[212:215], v[14:17]
	v_mfma_f32_16x16x32_bf16 v[10:13], v[164:167], v[212:215], v[10:13]
	v_mfma_f32_16x16x32_bf16 v[62:65], v[158:161], v[192:195], v[62:65]
	v_mfma_f32_16x16x32_bf16 v[58:61], v[168:171], v[192:195], v[58:61]
	v_mfma_f32_16x16x32_bf16 v[46:49], v[158:161], v[200:203], v[46:49]
	v_mfma_f32_16x16x32_bf16 v[42:45], v[168:171], v[200:203], v[42:45]
	v_mfma_f32_16x16x32_bf16 v[30:33], v[158:161], v[208:211], v[30:33]
	v_mfma_f32_16x16x32_bf16 v[26:29], v[168:171], v[208:211], v[26:29]
	v_mfma_f32_16x16x32_bf16 v[14:17], v[158:161], v[216:219], v[14:17]
	v_mfma_f32_16x16x32_bf16 v[10:13], v[168:171], v[216:219], v[10:13]
	v_mfma_f32_16x16x32_bf16 v[54:57], v[172:175], v[188:191], v[54:57]
	v_mfma_f32_16x16x32_bf16 v[50:53], v[180:183], v[188:191], v[50:53]
	v_mfma_f32_16x16x32_bf16 v[38:41], v[172:175], v[196:199], v[38:41]
	v_mfma_f32_16x16x32_bf16 v[34:37], v[180:183], v[196:199], v[34:37]
	v_mfma_f32_16x16x32_bf16 v[22:25], v[172:175], v[204:207], v[22:25]
	v_mfma_f32_16x16x32_bf16 v[18:21], v[180:183], v[204:207], v[18:21]
	v_mfma_f32_16x16x32_bf16 v[6:9], v[172:175], v[212:215], v[6:9]
	v_mfma_f32_16x16x32_bf16 v[2:5], v[180:183], v[212:215], v[2:5]
	v_mfma_f32_16x16x32_bf16 v[54:57], v[176:179], v[192:195], v[54:57]
	v_mfma_f32_16x16x32_bf16 v[50:53], v[184:187], v[192:195], v[50:53]
	v_mfma_f32_16x16x32_bf16 v[38:41], v[176:179], v[200:203], v[38:41]
	v_mfma_f32_16x16x32_bf16 v[34:37], v[184:187], v[200:203], v[34:37]
	v_mfma_f32_16x16x32_bf16 v[22:25], v[176:179], v[208:211], v[22:25]
	v_mfma_f32_16x16x32_bf16 v[18:21], v[184:187], v[208:211], v[18:21]
	v_mfma_f32_16x16x32_bf16 v[6:9], v[176:179], v[216:219], v[6:9]
	v_mfma_f32_16x16x32_bf16 v[2:5], v[184:187], v[216:219], v[2:5]
	s_barrier
	s_add_i32 s23, 0, 0x18000
	v_add_u32_e32 v153, s23, v148
	s_add_i32 s35, 0, 0x1c000
	ds_read_b128 v[154:157], v153
	ds_read_b128 v[158:161], v153 offset:1024
	ds_read_b128 v[164:167], v153 offset:2048
	ds_read_b128 v[168:171], v153 offset:3072
	v_add_u32_e32 v153, s35, v148
	ds_read_b128 v[172:175], v153
	ds_read_b128 v[176:179], v153 offset:1024
	ds_read_b128 v[180:183], v153 offset:2048
	ds_read_b128 v[184:187], v153 offset:3072
	s_add_u32 s24, s46, 0x80000
	s_addc_u32 s25, s47, 0
	s_mov_b32 m0, s50
	v_lshl_add_u64 v[226:227], s[24:25], 0, v[130:131]
	ds_read_b128 v[188:191], v152 offset:32768
	ds_read_b128 v[192:195], v152 offset:33792
	ds_read_b128 v[196:199], v152 offset:34816
	ds_read_b128 v[200:203], v152 offset:35840
	ds_read_b128 v[204:207], v152 offset:36864
	ds_read_b128 v[208:211], v152 offset:37888
	ds_read_b128 v[212:215], v152 offset:38912
	ds_read_b128 v[216:219], v152 offset:39936
	global_load_lds_dwordx4 v[226:227], off
	v_lshl_add_u64 v[226:227], s[24:25], 0, v[134:135]
	s_mov_b32 m0, s51
	s_nop 0
	global_load_lds_dwordx4 v[226:227], off
	s_waitcnt vmcnt(8)
	s_waitcnt lgkmcnt(0)
	s_barrier
	s_waitcnt lgkmcnt(0)
	v_mfma_f32_16x16x32_bf16 v[126:129], v[154:157], v[188:191], v[126:129]
	v_mfma_f32_16x16x32_bf16 v[122:125], v[164:167], v[188:191], v[122:125]
	v_mfma_f32_16x16x32_bf16 v[110:113], v[154:157], v[196:199], v[110:113]
	v_mfma_f32_16x16x32_bf16 v[106:109], v[164:167], v[196:199], v[106:109]
	v_mfma_f32_16x16x32_bf16 v[94:97], v[154:157], v[204:207], v[94:97]
	v_mfma_f32_16x16x32_bf16 v[90:93], v[164:167], v[204:207], v[90:93]
	v_mfma_f32_16x16x32_bf16 v[78:81], v[154:157], v[212:215], v[78:81]
	v_mfma_f32_16x16x32_bf16 v[74:77], v[164:167], v[212:215], v[74:77]
	v_mfma_f32_16x16x32_bf16 v[126:129], v[158:161], v[192:195], v[126:129]
	v_mfma_f32_16x16x32_bf16 v[122:125], v[168:171], v[192:195], v[122:125]
	v_mfma_f32_16x16x32_bf16 v[110:113], v[158:161], v[200:203], v[110:113]
	v_mfma_f32_16x16x32_bf16 v[106:109], v[168:171], v[200:203], v[106:109]
	v_mfma_f32_16x16x32_bf16 v[94:97], v[158:161], v[208:211], v[94:97]
	v_mfma_f32_16x16x32_bf16 v[90:93], v[168:171], v[208:211], v[90:93]
	v_mfma_f32_16x16x32_bf16 v[78:81], v[158:161], v[216:219], v[78:81]
	v_mfma_f32_16x16x32_bf16 v[74:77], v[168:171], v[216:219], v[74:77]
	v_mfma_f32_16x16x32_bf16 v[118:121], v[172:175], v[188:191], v[118:121]
	v_mfma_f32_16x16x32_bf16 v[114:117], v[180:183], v[188:191], v[114:117]
	v_mfma_f32_16x16x32_bf16 v[102:105], v[172:175], v[196:199], v[102:105]
	v_mfma_f32_16x16x32_bf16 v[98:101], v[180:183], v[196:199], v[98:101]
	v_mfma_f32_16x16x32_bf16 v[86:89], v[172:175], v[204:207], v[86:89]
	v_mfma_f32_16x16x32_bf16 v[82:85], v[180:183], v[204:207], v[82:85]
	v_mfma_f32_16x16x32_bf16 v[70:73], v[172:175], v[212:215], v[70:73]
	v_mfma_f32_16x16x32_bf16 v[66:69], v[180:183], v[212:215], v[66:69]
	v_mfma_f32_16x16x32_bf16 v[118:121], v[176:179], v[192:195], v[118:121]
	v_mfma_f32_16x16x32_bf16 v[114:117], v[184:187], v[192:195], v[114:117]
	v_mfma_f32_16x16x32_bf16 v[102:105], v[176:179], v[200:203], v[102:105]
	v_mfma_f32_16x16x32_bf16 v[98:101], v[184:187], v[200:203], v[98:101]
	v_mfma_f32_16x16x32_bf16 v[86:89], v[176:179], v[208:211], v[86:89]
	v_mfma_f32_16x16x32_bf16 v[82:85], v[184:187], v[208:211], v[82:85]
	v_mfma_f32_16x16x32_bf16 v[70:73], v[176:179], v[216:219], v[70:73]
	v_mfma_f32_16x16x32_bf16 v[66:69], v[184:187], v[216:219], v[66:69]
	s_barrier
	s_add_i32 s23, s23, s48
	v_lshl_add_u64 v[146:147], v[146:147], 0, s[8:9]
	s_mov_b32 m0, s23
	ds_read_b128 v[188:191], v152 offset:49152
	ds_read_b128 v[192:195], v152 offset:50176
	ds_read_b128 v[196:199], v152 offset:51200
	ds_read_b128 v[200:203], v152 offset:52224
	ds_read_b128 v[204:207], v152 offset:53248
	ds_read_b128 v[208:211], v152 offset:54272
	ds_read_b128 v[212:215], v152 offset:55296
	ds_read_b128 v[216:219], v152 offset:56320
	global_load_lds_dwordx4 v[146:147], off
	s_add_i32 m0, s23, 0x2000
	s_add_u32 s24, s44, 0x80080
	v_lshl_add_u64 v[146:147], v[220:221], 0, s[8:9]
	s_addc_u32 s25, s45, 0
	s_add_i32 s23, s35, s48
	global_load_lds_dwordx4 v[146:147], off
	v_lshl_add_u64 v[146:147], s[24:25], 0, v[132:133]
	s_mov_b32 m0, s23
	s_nop 0
	global_load_lds_dwordx4 v[146:147], off
	v_lshl_add_u64 v[146:147], s[24:25], 0, v[136:137]
	s_add_i32 m0, s23, 0x2000
	s_nop 0
	global_load_lds_dwordx4 v[146:147], off
	v_lshl_add_u64 v[146:147], v[222:223], 0, s[8:9]
	s_mov_b32 m0, s53
	s_nop 0
	global_load_lds_dwordx4 v[146:147], off
	v_lshl_add_u64 v[146:147], v[224:225], 0, s[8:9]
	s_mov_b32 m0, s54
	s_nop 0
	global_load_lds_dwordx4 v[146:147], off
	s_waitcnt vmcnt(8)
	s_waitcnt lgkmcnt(0)
	s_barrier
	s_waitcnt lgkmcnt(0)
	v_mfma_f32_16x16x32_bf16 v[62:65], v[154:157], v[188:191], v[62:65]
	v_mfma_f32_16x16x32_bf16 v[58:61], v[164:167], v[188:191], v[58:61]
	v_mfma_f32_16x16x32_bf16 v[46:49], v[154:157], v[196:199], v[46:49]
	v_mfma_f32_16x16x32_bf16 v[42:45], v[164:167], v[196:199], v[42:45]
	v_mfma_f32_16x16x32_bf16 v[30:33], v[154:157], v[204:207], v[30:33]
	v_mfma_f32_16x16x32_bf16 v[26:29], v[164:167], v[204:207], v[26:29]
	v_mfma_f32_16x16x32_bf16 v[14:17], v[154:157], v[212:215], v[14:17]
	v_mfma_f32_16x16x32_bf16 v[10:13], v[164:167], v[212:215], v[10:13]
	v_mfma_f32_16x16x32_bf16 v[62:65], v[158:161], v[192:195], v[62:65]
	v_mfma_f32_16x16x32_bf16 v[58:61], v[168:171], v[192:195], v[58:61]
	v_mfma_f32_16x16x32_bf16 v[46:49], v[158:161], v[200:203], v[46:49]
	v_mfma_f32_16x16x32_bf16 v[42:45], v[168:171], v[200:203], v[42:45]
	v_mfma_f32_16x16x32_bf16 v[30:33], v[158:161], v[208:211], v[30:33]
	v_mfma_f32_16x16x32_bf16 v[26:29], v[168:171], v[208:211], v[26:29]
	v_mfma_f32_16x16x32_bf16 v[14:17], v[158:161], v[216:219], v[14:17]
	v_mfma_f32_16x16x32_bf16 v[10:13], v[168:171], v[216:219], v[10:13]
	v_mfma_f32_16x16x32_bf16 v[54:57], v[172:175], v[188:191], v[54:57]
	v_mfma_f32_16x16x32_bf16 v[50:53], v[180:183], v[188:191], v[50:53]
	v_mfma_f32_16x16x32_bf16 v[38:41], v[172:175], v[196:199], v[38:41]
	v_mfma_f32_16x16x32_bf16 v[34:37], v[180:183], v[196:199], v[34:37]
	v_mfma_f32_16x16x32_bf16 v[22:25], v[172:175], v[204:207], v[22:25]
	v_mfma_f32_16x16x32_bf16 v[18:21], v[180:183], v[204:207], v[18:21]
	v_mfma_f32_16x16x32_bf16 v[6:9], v[172:175], v[212:215], v[6:9]
	v_mfma_f32_16x16x32_bf16 v[2:5], v[180:183], v[212:215], v[2:5]
	v_mfma_f32_16x16x32_bf16 v[54:57], v[176:179], v[192:195], v[54:57]
	v_mfma_f32_16x16x32_bf16 v[50:53], v[184:187], v[192:195], v[50:53]
	v_mfma_f32_16x16x32_bf16 v[38:41], v[176:179], v[200:203], v[38:41]
	v_mfma_f32_16x16x32_bf16 v[34:37], v[184:187], v[200:203], v[34:37]
	v_mfma_f32_16x16x32_bf16 v[22:25], v[176:179], v[208:211], v[22:25]
	v_mfma_f32_16x16x32_bf16 v[18:21], v[184:187], v[208:211], v[18:21]
	v_mfma_f32_16x16x32_bf16 v[6:9], v[176:179], v[216:219], v[6:9]
	v_mfma_f32_16x16x32_bf16 v[2:5], v[184:187], v[216:219], v[2:5]
	s_barrier
	s_add_i32 s64, s64, 2
	s_add_u32 s42, s42, 0x100
	s_addc_u32 s43, s43, 0
	s_add_u32 s62, s62, 0x100
	s_addc_u32 s63, s63, 0
	s_cmp_gt_u32 s64, 29
	s_cbranch_scc0 .LBB0_1149
	s_and_b64 vcc, exec, s[10:11]
	s_cbranch_vccz .LBB0_1152
	s_barrier

.LBB0_1248:
	ds_read_b128 v[146:149], v159
	ds_read_b128 v[150:153], v159 offset:1024
	ds_read_b128 v[164:167], v159 offset:2048
	ds_read_b128 v[168:171], v159 offset:3072
	ds_read_b128 v[172:175], v160
	ds_read_b128 v[176:179], v160 offset:1024
	ds_read_b128 v[180:183], v160 offset:2048
	ds_read_b128 v[184:187], v160 offset:3072
	s_add_i32 s25, s24, 2
	s_add_u32 s42, s38, 0xffea0080
	s_addc_u32 s43, s39, -1
	s_cmp_eq_u32 s70, s24
	s_cselect_b32 s45, s66, s43
	s_cselect_b32 s44, s67, s42
	s_cselect_b32 s43, s68, s72
	s_cselect_b32 s42, s69, s71
	s_cselect_b64 s[100:101], s[28:29], -1
	v_lshl_add_u64 v[154:155], s[38:39], 0, v[138:139]
	s_add_i32 m0, s33, 0xc000
	ds_read_b128 v[188:191], v161
	ds_read_b128 v[192:195], v161 offset:1024
	ds_read_b128 v[196:199], v161 offset:2048
	ds_read_b128 v[200:203], v161 offset:3072
	ds_read_b128 v[204:207], v161 offset:4096
	ds_read_b128 v[208:211], v161 offset:5120
	ds_read_b128 v[212:215], v161 offset:6144
	ds_read_b128 v[216:219], v161 offset:7168
	global_load_lds_dwordx4 v[154:155], off
	v_lshl_add_u64 v[154:155], s[38:39], 0, v[140:141]
	s_add_i32 m0, s33, 0xe000
	s_nop 0
	global_load_lds_dwordx4 v[154:155], off
	s_waitcnt vmcnt(8)
	s_waitcnt lgkmcnt(0)
	s_barrier
	s_waitcnt lgkmcnt(0)
	v_mfma_f32_16x16x32_bf16 v[76:79], v[146:149], v[188:191], v[76:79]
	v_mfma_f32_16x16x32_bf16 v[72:75], v[164:167], v[188:191], v[72:75]
	v_mfma_f32_16x16x32_bf16 v[64:67], v[146:149], v[196:199], v[64:67]
	v_mfma_f32_16x16x32_bf16 v[56:59], v[164:167], v[196:199], v[56:59]
	v_mfma_f32_16x16x32_bf16 v[52:55], v[146:149], v[204:207], v[52:55]
	v_mfma_f32_16x16x32_bf16 v[44:47], v[164:167], v[204:207], v[44:47]
	v_mfma_f32_16x16x32_bf16 v[36:39], v[146:149], v[212:215], v[36:39]
	v_mfma_f32_16x16x32_bf16 v[28:31], v[164:167], v[212:215], v[28:31]
	v_mfma_f32_16x16x32_bf16 v[76:79], v[150:153], v[192:195], v[76:79]
	v_mfma_f32_16x16x32_bf16 v[72:75], v[168:171], v[192:195], v[72:75]
	v_mfma_f32_16x16x32_bf16 v[64:67], v[150:153], v[200:203], v[64:67]
	v_mfma_f32_16x16x32_bf16 v[56:59], v[168:171], v[200:203], v[56:59]
	v_mfma_f32_16x16x32_bf16 v[52:55], v[150:153], v[208:211], v[52:55]
	v_mfma_f32_16x16x32_bf16 v[44:47], v[168:171], v[208:211], v[44:47]
	v_mfma_f32_16x16x32_bf16 v[36:39], v[150:153], v[216:219], v[36:39]
	v_mfma_f32_16x16x32_bf16 v[28:31], v[168:171], v[216:219], v[28:31]
	v_mfma_f32_16x16x32_bf16 v[48:51], v[172:175], v[188:191], v[48:51]
	v_mfma_f32_16x16x32_bf16 v[40:43], v[180:183], v[188:191], v[40:43]
	v_mfma_f32_16x16x32_bf16 v[32:35], v[172:175], v[196:199], v[32:35]
	v_mfma_f32_16x16x32_bf16 v[24:27], v[180:183], v[196:199], v[24:27]
	v_mfma_f32_16x16x32_bf16 v[20:23], v[172:175], v[204:207], v[20:23]
	v_mfma_f32_16x16x32_bf16 v[16:19], v[180:183], v[204:207], v[16:19]
	v_mfma_f32_16x16x32_bf16 v[8:11], v[172:175], v[212:215], v[8:11]
	v_mfma_f32_16x16x32_bf16 v[4:7], v[180:183], v[212:215], v[4:7]
	v_mfma_f32_16x16x32_bf16 v[48:51], v[176:179], v[192:195], v[48:51]
	v_mfma_f32_16x16x32_bf16 v[40:43], v[184:187], v[192:195], v[40:43]
	v_mfma_f32_16x16x32_bf16 v[32:35], v[176:179], v[200:203], v[32:35]
	v_mfma_f32_16x16x32_bf16 v[24:27], v[184:187], v[200:203], v[24:27]
	v_mfma_f32_16x16x32_bf16 v[20:23], v[176:179], v[208:211], v[20:23]
	v_mfma_f32_16x16x32_bf16 v[16:19], v[184:187], v[208:211], v[16:19]
	v_mfma_f32_16x16x32_bf16 v[8:11], v[176:179], v[216:219], v[8:11]
	v_mfma_f32_16x16x32_bf16 v[4:7], v[184:187], v[216:219], v[4:7]
	s_barrier
	s_add_i32 s24, s58, s23
	v_lshl_add_u64 v[154:155], s[42:43], 0, v[130:131]
	s_mov_b32 m0, s24
	ds_read_b128 v[188:191], v161 offset:16384
	ds_read_b128 v[192:195], v161 offset:17408
	ds_read_b128 v[196:199], v161 offset:18432
	ds_read_b128 v[200:203], v161 offset:19456
	ds_read_b128 v[204:207], v161 offset:20480
	ds_read_b128 v[208:211], v161 offset:21504
	ds_read_b128 v[212:215], v161 offset:22528
	ds_read_b128 v[216:219], v161 offset:23552
	global_load_lds_dwordx4 v[154:155], off
	s_add_i32 m0, s24, 0x2000
	s_add_u32 s74, s42, 0x160000
	v_lshl_add_u64 v[220:221], s[42:43], 0, v[134:135]
	s_addc_u32 s75, s43, 0
	s_add_i32 s24, s59, s23
	global_load_lds_dwordx4 v[220:221], off
	v_lshl_add_u64 v[222:223], s[74:75], 0, v[130:131]
	s_mov_b32 m0, s24
	v_lshl_add_u64 v[224:225], s[44:45], 0, v[132:133]
	global_load_lds_dwordx4 v[222:223], off
	v_lshl_add_u64 v[222:223], s[74:75], 0, v[134:135]
	s_add_i32 m0, s24, 0x2000
	s_nop 0
	global_load_lds_dwordx4 v[222:223], off
	v_lshl_add_u64 v[222:223], s[44:45], 0, v[128:129]
	s_mov_b32 m0, s33
	s_nop 0
	global_load_lds_dwordx4 v[222:223], off
	s_mov_b32 m0, s46
	s_nop 0
	global_load_lds_dwordx4 v[224:225], off
	s_waitcnt vmcnt(8)
	s_waitcnt lgkmcnt(0)
	s_barrier
	s_waitcnt lgkmcnt(0)
	v_mfma_f32_16x16x32_bf16 v[124:127], v[146:149], v[188:191], v[124:127]
	v_mfma_f32_16x16x32_bf16 v[120:123], v[164:167], v[188:191], v[120:123]
	v_mfma_f32_16x16x32_bf16 v[108:111], v[146:149], v[196:199], v[108:111]
	v_mfma_f32_16x16x32_bf16 v[104:107], v[164:167], v[196:199], v[104:107]
	v_mfma_f32_16x16x32_bf16 v[92:95], v[146:149], v[204:207], v[92:95]
	v_mfma_f32_16x16x32_bf16 v[88:91], v[164:167], v[204:207], v[88:91]
	v_mfma_f32_16x16x32_bf16 v[68:71], v[146:149], v[212:215], v[68:71]
	v_mfma_f32_16x16x32_bf16 v[60:63], v[164:167], v[212:215], v[60:63]
	v_mfma_f32_16x16x32_bf16 v[124:127], v[150:153], v[192:195], v[124:127]
	v_mfma_f32_16x16x32_bf16 v[120:123], v[168:171], v[192:195], v[120:123]
	v_mfma_f32_16x16x32_bf16 v[108:111], v[150:153], v[200:203], v[108:111]
	v_mfma_f32_16x16x32_bf16 v[104:107], v[168:171], v[200:203], v[104:107]
	v_mfma_f32_16x16x32_bf16 v[92:95], v[150:153], v[208:211], v[92:95]
	v_mfma_f32_16x16x32_bf16 v[88:91], v[168:171], v[208:211], v[88:91]
	v_mfma_f32_16x16x32_bf16 v[68:71], v[150:153], v[216:219], v[68:71]
	v_mfma_f32_16x16x32_bf16 v[60:63], v[168:171], v[216:219], v[60:63]
	v_mfma_f32_16x16x32_bf16 v[116:119], v[172:175], v[188:191], v[116:119]
	v_mfma_f32_16x16x32_bf16 v[112:115], v[180:183], v[188:191], v[112:115]
	v_mfma_f32_16x16x32_bf16 v[100:103], v[172:175], v[196:199], v[100:103]
	v_mfma_f32_16x16x32_bf16 v[96:99], v[180:183], v[196:199], v[96:99]
	v_mfma_f32_16x16x32_bf16 v[84:87], v[172:175], v[204:207], v[84:87]
	v_mfma_f32_16x16x32_bf16 v[80:83], v[180:183], v[204:207], v[80:83]
	v_mfma_f32_16x16x32_bf16 v[12:15], v[172:175], v[212:215], v[12:15]
	v_mfma_f32_16x16x32_bf16 v[0:3], v[180:183], v[212:215], v[0:3]
	v_mfma_f32_16x16x32_bf16 v[116:119], v[176:179], v[192:195], v[116:119]
	v_mfma_f32_16x16x32_bf16 v[112:115], v[184:187], v[192:195], v[112:115]
	v_mfma_f32_16x16x32_bf16 v[100:103], v[176:179], v[200:203], v[100:103]
	v_mfma_f32_16x16x32_bf16 v[96:99], v[184:187], v[200:203], v[96:99]
	v_mfma_f32_16x16x32_bf16 v[84:87], v[176:179], v[208:211], v[84:87]
	v_mfma_f32_16x16x32_bf16 v[80:83], v[184:187], v[208:211], v[80:83]
	v_mfma_f32_16x16x32_bf16 v[12:15], v[176:179], v[216:219], v[12:15]
	v_mfma_f32_16x16x32_bf16 v[0:3], v[184:187], v[216:219], v[0:3]
	s_barrier
	s_add_i32 s24, 0, 0x18000
	v_add_u32_e32 v163, s24, v157
	s_add_i32 s73, 0, 0x1c000
	ds_read_b128 v[146:149], v163
	ds_read_b128 v[150:153], v163 offset:1024
	ds_read_b128 v[164:167], v163 offset:2048
	ds_read_b128 v[168:171], v163 offset:3072
	v_add_u32_e32 v163, s73, v157
	ds_read_b128 v[172:175], v163
	ds_read_b128 v[176:179], v163 offset:1024
	ds_read_b128 v[180:183], v163 offset:2048
	ds_read_b128 v[184:187], v163 offset:3072
	s_add_u32 s44, s44, 0x160000
	s_addc_u32 s45, s45, 0
	s_mov_b32 m0, s47
	v_lshl_add_u64 v[226:227], s[44:45], 0, v[128:129]
	ds_read_b128 v[188:191], v161 offset:32768
	ds_read_b128 v[192:195], v161 offset:33792
	ds_read_b128 v[196:199], v161 offset:34816
	ds_read_b128 v[200:203], v161 offset:35840
	ds_read_b128 v[204:207], v161 offset:36864
	ds_read_b128 v[208:211], v161 offset:37888
	ds_read_b128 v[212:215], v161 offset:38912
	ds_read_b128 v[216:219], v161 offset:39936
	s_mov_b64 exec, s[100:101]
	global_load_lds_dwordx4 v[226:227], off
	s_mov_b64 exec, -1
	v_lshl_add_u64 v[226:227], s[44:45], 0, v[132:133]
	s_mov_b32 m0, s48
	s_nop 0
	s_mov_b64 exec, s[100:101]
	global_load_lds_dwordx4 v[226:227], off
	s_mov_b64 exec, -1
	s_waitcnt vmcnt(8)
	s_waitcnt lgkmcnt(0)
	s_barrier
	s_waitcnt lgkmcnt(0)
	v_mfma_f32_16x16x32_bf16 v[76:79], v[146:149], v[188:191], v[76:79]
	v_mfma_f32_16x16x32_bf16 v[72:75], v[164:167], v[188:191], v[72:75]
	v_mfma_f32_16x16x32_bf16 v[64:67], v[146:149], v[196:199], v[64:67]
	v_mfma_f32_16x16x32_bf16 v[56:59], v[164:167], v[196:199], v[56:59]
	v_mfma_f32_16x16x32_bf16 v[52:55], v[146:149], v[204:207], v[52:55]
	v_mfma_f32_16x16x32_bf16 v[44:47], v[164:167], v[204:207], v[44:47]
	v_mfma_f32_16x16x32_bf16 v[36:39], v[146:149], v[212:215], v[36:39]
	v_mfma_f32_16x16x32_bf16 v[28:31], v[164:167], v[212:215], v[28:31]
	v_mfma_f32_16x16x32_bf16 v[76:79], v[150:153], v[192:195], v[76:79]
	v_mfma_f32_16x16x32_bf16 v[72:75], v[168:171], v[192:195], v[72:75]
	v_mfma_f32_16x16x32_bf16 v[64:67], v[150:153], v[200:203], v[64:67]
	v_mfma_f32_16x16x32_bf16 v[56:59], v[168:171], v[200:203], v[56:59]
	v_mfma_f32_16x16x32_bf16 v[52:55], v[150:153], v[208:211], v[52:55]
	v_mfma_f32_16x16x32_bf16 v[44:47], v[168:171], v[208:211], v[44:47]
	v_mfma_f32_16x16x32_bf16 v[36:39], v[150:153], v[216:219], v[36:39]
	v_mfma_f32_16x16x32_bf16 v[28:31], v[168:171], v[216:219], v[28:31]
	v_mfma_f32_16x16x32_bf16 v[48:51], v[172:175], v[188:191], v[48:51]
	v_mfma_f32_16x16x32_bf16 v[40:43], v[180:183], v[188:191], v[40:43]
	v_mfma_f32_16x16x32_bf16 v[32:35], v[172:175], v[196:199], v[32:35]
	v_mfma_f32_16x16x32_bf16 v[24:27], v[180:183], v[196:199], v[24:27]
	v_mfma_f32_16x16x32_bf16 v[20:23], v[172:175], v[204:207], v[20:23]
	v_mfma_f32_16x16x32_bf16 v[16:19], v[180:183], v[204:207], v[16:19]
	v_mfma_f32_16x16x32_bf16 v[8:11], v[172:175], v[212:215], v[8:11]
	v_mfma_f32_16x16x32_bf16 v[4:7], v[180:183], v[212:215], v[4:7]
	v_mfma_f32_16x16x32_bf16 v[48:51], v[176:179], v[192:195], v[48:51]
	v_mfma_f32_16x16x32_bf16 v[40:43], v[184:187], v[192:195], v[40:43]
	v_mfma_f32_16x16x32_bf16 v[32:35], v[176:179], v[200:203], v[32:35]
	v_mfma_f32_16x16x32_bf16 v[24:27], v[184:187], v[200:203], v[24:27]
	v_mfma_f32_16x16x32_bf16 v[20:23], v[176:179], v[208:211], v[20:23]
	v_mfma_f32_16x16x32_bf16 v[16:19], v[184:187], v[208:211], v[16:19]
	v_mfma_f32_16x16x32_bf16 v[8:11], v[176:179], v[216:219], v[8:11]
	v_mfma_f32_16x16x32_bf16 v[4:7], v[184:187], v[216:219], v[4:7]
	s_barrier
	s_add_i32 s24, s24, s23
	v_lshl_add_u64 v[154:155], v[154:155], 0, s[8:9]
	s_mov_b32 m0, s24
	ds_read_b128 v[188:191], v161 offset:49152
	ds_read_b128 v[192:195], v161 offset:50176
	ds_read_b128 v[196:199], v161 offset:51200
	ds_read_b128 v[200:203], v161 offset:52224
	ds_read_b128 v[204:207], v161 offset:53248
	ds_read_b128 v[208:211], v161 offset:54272
	ds_read_b128 v[212:215], v161 offset:55296
	ds_read_b128 v[216:219], v161 offset:56320
	s_mov_b64 exec, s[100:101]
	global_load_lds_dwordx4 v[154:155], off
	s_mov_b64 exec, -1
	s_add_i32 m0, s24, 0x2000
	s_add_u32 s42, s42, 0x160080
	v_lshl_add_u64 v[154:155], v[220:221], 0, s[8:9]
	s_addc_u32 s43, s43, 0
	s_add_i32 s24, s73, s23
	s_mov_b64 exec, s[100:101]
	global_load_lds_dwordx4 v[154:155], off
	s_mov_b64 exec, -1
	v_lshl_add_u64 v[154:155], s[42:43], 0, v[130:131]
	s_mov_b32 m0, s24
	s_nop 0
	s_mov_b64 exec, s[100:101]
	global_load_lds_dwordx4 v[154:155], off
	s_mov_b64 exec, -1
	v_lshl_add_u64 v[154:155], s[42:43], 0, v[134:135]
	s_add_i32 m0, s24, 0x2000
	s_nop 0
	s_mov_b64 exec, s[100:101]
	global_load_lds_dwordx4 v[154:155], off
	s_mov_b64 exec, -1
	v_lshl_add_u64 v[154:155], v[222:223], 0, s[8:9]
	s_mov_b32 m0, s54
	s_nop 0
	s_mov_b64 exec, s[100:101]
	global_load_lds_dwordx4 v[154:155], off
	s_mov_b64 exec, -1
	v_lshl_add_u64 v[154:155], v[224:225], 0, s[8:9]
	s_mov_b32 m0, s55
	s_nop 0
	s_mov_b64 exec, s[100:101]
	global_load_lds_dwordx4 v[154:155], off
	s_mov_b64 exec, -1
	s_waitcnt vmcnt(8)
	s_waitcnt lgkmcnt(0)
	s_barrier
	s_waitcnt lgkmcnt(0)
	v_mfma_f32_16x16x32_bf16 v[124:127], v[146:149], v[188:191], v[124:127]
	v_mfma_f32_16x16x32_bf16 v[120:123], v[164:167], v[188:191], v[120:123]
	v_mfma_f32_16x16x32_bf16 v[108:111], v[146:149], v[196:199], v[108:111]
	v_mfma_f32_16x16x32_bf16 v[104:107], v[164:167], v[196:199], v[104:107]
	v_mfma_f32_16x16x32_bf16 v[92:95], v[146:149], v[204:207], v[92:95]
	v_mfma_f32_16x16x32_bf16 v[88:91], v[164:167], v[204:207], v[88:91]
	v_mfma_f32_16x16x32_bf16 v[68:71], v[146:149], v[212:215], v[68:71]
	v_mfma_f32_16x16x32_bf16 v[60:63], v[164:167], v[212:215], v[60:63]
	v_mfma_f32_16x16x32_bf16 v[124:127], v[150:153], v[192:195], v[124:127]
	v_mfma_f32_16x16x32_bf16 v[120:123], v[168:171], v[192:195], v[120:123]
	v_mfma_f32_16x16x32_bf16 v[108:111], v[150:153], v[200:203], v[108:111]
	v_mfma_f32_16x16x32_bf16 v[104:107], v[168:171], v[200:203], v[104:107]
	v_mfma_f32_16x16x32_bf16 v[92:95], v[150:153], v[208:211], v[92:95]
	v_mfma_f32_16x16x32_bf16 v[88:91], v[168:171], v[208:211], v[88:91]
	v_mfma_f32_16x16x32_bf16 v[68:71], v[150:153], v[216:219], v[68:71]
	v_mfma_f32_16x16x32_bf16 v[60:63], v[168:171], v[216:219], v[60:63]
	v_mfma_f32_16x16x32_bf16 v[116:119], v[172:175], v[188:191], v[116:119]
	v_mfma_f32_16x16x32_bf16 v[112:115], v[180:183], v[188:191], v[112:115]
	v_mfma_f32_16x16x32_bf16 v[100:103], v[172:175], v[196:199], v[100:103]
	v_mfma_f32_16x16x32_bf16 v[96:99], v[180:183], v[196:199], v[96:99]
	v_mfma_f32_16x16x32_bf16 v[84:87], v[172:175], v[204:207], v[84:87]
	v_mfma_f32_16x16x32_bf16 v[80:83], v[180:183], v[204:207], v[80:83]
	v_mfma_f32_16x16x32_bf16 v[12:15], v[172:175], v[212:215], v[12:15]
	v_mfma_f32_16x16x32_bf16 v[0:3], v[180:183], v[212:215], v[0:3]
	v_mfma_f32_16x16x32_bf16 v[116:119], v[176:179], v[192:195], v[116:119]
	v_mfma_f32_16x16x32_bf16 v[112:115], v[184:187], v[192:195], v[112:115]
	v_mfma_f32_16x16x32_bf16 v[100:103], v[176:179], v[200:203], v[100:103]
	v_mfma_f32_16x16x32_bf16 v[96:99], v[184:187], v[200:203], v[96:99]
	v_mfma_f32_16x16x32_bf16 v[84:87], v[176:179], v[208:211], v[84:87]
	v_mfma_f32_16x16x32_bf16 v[80:83], v[184:187], v[208:211], v[80:83]
	v_mfma_f32_16x16x32_bf16 v[12:15], v[176:179], v[216:219], v[12:15]
	v_mfma_f32_16x16x32_bf16 v[0:3], v[184:187], v[216:219], v[0:3]
	s_barrier
	s_add_u32 s38, s38, 0x100
	s_addc_u32 s39, s39, 0
	s_add_u32 s71, s71, 0x100
	s_addc_u32 s72, s72, 0
	s_cmp_ge_i32 s25, s65
	s_mov_b32 s24, s25
	s_cbranch_scc0 .LBB0_1248
	s_and_b64 vcc, exec, s[10:11]
	s_cbranch_vccz .LBB0_1251
	s_barrier
